# row passes (phases 1,5,8,13,16): hoisted the per-group modulation/LN-param loads above the stores with counted vmcnt waits; select: exec-masked hist passes 1-2, fast final
# speedup vs baseline: 1.0472x; 1.0060x over previous
.LBB0_358:
	global_load_dwordx4 v[16:19], v[6:7], off offset:-4096
	v_ashrrev_i32_e32 v1, 13, v0
	v_mul_i32_i24_e32 v20, 6, v1
	v_ashrrev_i32_e32 v21, 31, v20
	v_lshlrev_b64 v[20:21], 13, v[20:21]
	v_lshl_add_u64 v[56:57], s[6:7], 0, v[20:21]
	v_lshl_add_u64 v[58:59], s[30:31], 0, v[20:21]
	v_lshl_add_u64 v[60:61], v[56:57], 0, v[2:3]
	v_lshl_add_u64 v[62:63], v[58:59], 0, v[2:3]
	global_load_dwordx4 v[20:23], v[60:61], off
	global_load_dwordx4 v[24:27], v[62:63], off
	global_load_dwordx4 v[28:31], v[6:7], off offset:-3072
	global_load_dwordx4 v[32:35], v[6:7], off offset:-2048
	global_load_dwordx4 v[36:39], v[6:7], off offset:-1024
	global_load_dwordx4 v[40:43], v[6:7], off
	global_load_dwordx4 v[44:47], v[6:7], off offset:1024
	global_load_dwordx4 v[48:51], v[6:7], off offset:2048
	global_load_dwordx4 v[52:55], v[6:7], off offset:3072
	global_load_dwordx4 v[170:173], v[60:61], off offset:1024
	global_load_dwordx4 v[174:177], v[62:63], off offset:1024
	global_load_dwordx4 v[178:181], v[60:61], off offset:2048
	global_load_dwordx4 v[182:185], v[62:63], off offset:2048
	global_load_dwordx4 v[186:189], v[60:61], off offset:3072
	global_load_dwordx4 v[190:193], v[62:63], off offset:3072
	v_lshl_add_u64 v[198:199], v[56:57], 0, v[8:9]
	global_load_dwordx4 v[194:197], v[198:199], off
	v_lshl_add_u64 v[204:205], v[58:59], 0, v[8:9]
	global_load_dwordx4 v[200:203], v[204:205], off
	v_lshl_add_u64 v[210:211], v[56:57], 0, v[10:11]
	global_load_dwordx4 v[206:209], v[210:211], off
	v_lshl_add_u64 v[216:217], v[58:59], 0, v[10:11]
	global_load_dwordx4 v[212:215], v[216:217], off
	v_lshl_add_u64 v[222:223], v[56:57], 0, v[12:13]
	global_load_dwordx4 v[218:221], v[222:223], off
	v_lshl_add_u64 v[228:229], v[58:59], 0, v[12:13]
	global_load_dwordx4 v[224:227], v[228:229], off
	v_lshl_add_u64 v[234:235], v[56:57], 0, v[14:15]
	global_load_dwordx4 v[230:233], v[234:235], off
	v_lshl_add_u64 v[240:241], v[58:59], 0, v[14:15]
	global_load_dwordx4 v[236:239], v[240:241], off
	v_add_u32_e32 v0, s8, v0
	v_cmp_lt_i32_e32 vcc, s3, v0
	v_lshl_add_u64 v[6:7], v[6:7], 0, s[12:13]
	s_or_b64 s[14:15], vcc, s[14:15]
	s_waitcnt vmcnt(22)
	v_pk_add_f32 v[22:23], v[22:23], 1.0 op_sel_hi:[1,0]
	v_pk_add_f32 v[20:21], v[20:21], 1.0 op_sel_hi:[1,0]
	s_waitcnt vmcnt(21)
	v_pk_fma_f32 v[18:19], v[18:19], v[22:23], v[26:27]
	v_pk_fma_f32 v[16:17], v[16:17], v[20:21], v[24:25]
	v_cvt_pk_bf16_f32 v16, v16, v17
	v_cvt_pk_bf16_f32 v17, v18, v19
	global_store_dwordx2 v[4:5], v[16:17], off
	s_nop 0
	s_waitcnt vmcnt(14)
	v_pk_add_f32 v[18:19], v[172:173], 1.0 op_sel_hi:[1,0]
	v_pk_add_f32 v[16:17], v[170:171], 1.0 op_sel_hi:[1,0]
	s_waitcnt vmcnt(13)
	v_pk_fma_f32 v[18:19], v[30:31], v[18:19], v[176:177]
	v_pk_fma_f32 v[16:17], v[28:29], v[16:17], v[174:175]
	s_nop 0
	v_cvt_pk_bf16_f32 v16, v16, v17
	v_cvt_pk_bf16_f32 v17, v18, v19
	global_store_dwordx2 v[4:5], v[16:17], off offset:512
	s_nop 0
	s_waitcnt vmcnt(13)
	v_pk_add_f32 v[18:19], v[180:181], 1.0 op_sel_hi:[1,0]
	v_pk_add_f32 v[16:17], v[178:179], 1.0 op_sel_hi:[1,0]
	s_waitcnt vmcnt(12)
	v_pk_fma_f32 v[18:19], v[34:35], v[18:19], v[184:185]
	v_pk_fma_f32 v[16:17], v[32:33], v[16:17], v[182:183]
	s_nop 0
	v_cvt_pk_bf16_f32 v16, v16, v17
	v_cvt_pk_bf16_f32 v17, v18, v19
	global_store_dwordx2 v[4:5], v[16:17], off offset:1024
	s_nop 0
	s_waitcnt vmcnt(12)
	v_pk_add_f32 v[18:19], v[188:189], 1.0 op_sel_hi:[1,0]
	v_pk_add_f32 v[16:17], v[186:187], 1.0 op_sel_hi:[1,0]
	s_waitcnt vmcnt(11)
	v_pk_fma_f32 v[18:19], v[38:39], v[18:19], v[192:193]
	v_pk_fma_f32 v[16:17], v[36:37], v[16:17], v[190:191]
	s_nop 0
	v_cvt_pk_bf16_f32 v16, v16, v17
	v_cvt_pk_bf16_f32 v17, v18, v19
	global_store_dwordx2 v[4:5], v[16:17], off offset:1536
	s_nop 0
	s_waitcnt vmcnt(11)
	v_pk_add_f32 v[18:19], v[196:197], 1.0 op_sel_hi:[1,0]
	v_pk_add_f32 v[16:17], v[194:195], 1.0 op_sel_hi:[1,0]
	s_waitcnt vmcnt(10)
	v_pk_fma_f32 v[18:19], v[42:43], v[18:19], v[202:203]
	v_pk_fma_f32 v[16:17], v[40:41], v[16:17], v[200:201]
	s_nop 0
	v_cvt_pk_bf16_f32 v16, v16, v17
	v_cvt_pk_bf16_f32 v17, v18, v19
	global_store_dwordx2 v[4:5], v[16:17], off offset:2048
	s_nop 0
	s_waitcnt vmcnt(10)
	v_pk_add_f32 v[18:19], v[208:209], 1.0 op_sel_hi:[1,0]
	v_pk_add_f32 v[16:17], v[206:207], 1.0 op_sel_hi:[1,0]
	s_waitcnt vmcnt(9)
	v_pk_fma_f32 v[18:19], v[46:47], v[18:19], v[214:215]
	v_pk_fma_f32 v[16:17], v[44:45], v[16:17], v[212:213]
	s_nop 0
	v_cvt_pk_bf16_f32 v16, v16, v17
	v_cvt_pk_bf16_f32 v17, v18, v19
	global_store_dwordx2 v[4:5], v[16:17], off offset:2560
	s_nop 0
	s_waitcnt vmcnt(9)
	v_pk_add_f32 v[18:19], v[220:221], 1.0 op_sel_hi:[1,0]
	v_pk_add_f32 v[16:17], v[218:219], 1.0 op_sel_hi:[1,0]
	s_waitcnt vmcnt(8)
	v_pk_fma_f32 v[18:19], v[50:51], v[18:19], v[226:227]
	v_pk_fma_f32 v[16:17], v[48:49], v[16:17], v[224:225]
	s_nop 0
	v_cvt_pk_bf16_f32 v16, v16, v17
	v_cvt_pk_bf16_f32 v17, v18, v19
	global_store_dwordx2 v[4:5], v[16:17], off offset:3072
	s_nop 0
	s_waitcnt vmcnt(8)
	v_pk_add_f32 v[18:19], v[232:233], 1.0 op_sel_hi:[1,0]
	v_pk_add_f32 v[16:17], v[230:231], 1.0 op_sel_hi:[1,0]
	s_waitcnt vmcnt(7)
	v_pk_fma_f32 v[18:19], v[54:55], v[18:19], v[238:239]
	v_pk_fma_f32 v[16:17], v[52:53], v[16:17], v[236:237]
	s_nop 0
	v_cvt_pk_bf16_f32 v16, v16, v17
	v_cvt_pk_bf16_f32 v17, v18, v19
	global_store_dwordx2 v[4:5], v[16:17], off offset:3584
	v_lshl_add_u64 v[4:5], v[4:5], 0, s[10:11]
	s_andn2_b64 exec, exec, s[14:15]
	s_cbranch_execnz .LBB0_358

.LBB0_747:
	s_or_b64 exec, exec, s[4:5]
	v_ashrrev_i32_e32 v85, 13, v64
	v_mul_i32_i24_e32 v150, 6, v85
	v_ashrrev_i32_e32 v151, 31, v150
	v_lshlrev_b64 v[150:151], 13, v[150:151]
	v_lshl_add_u64 v[158:159], s[10:11], 0, v[150:151]
	v_lshl_add_u64 v[160:161], s[12:13], 0, v[150:151]
	v_lshl_add_u64 v[162:163], v[158:159], 0, v[66:67]
	global_load_dwordx4 v[150:153], v[162:163], off
	v_lshl_add_u64 v[164:165], v[160:161], 0, v[66:67]
	global_load_dwordx4 v[154:157], v[164:165], off
	v_mov_b32_e32 v166, v125
	v_mov_b32_e32 v167, v129
	v_mov_b32_e32 v168, v131
	v_mov_b32_e32 v169, v133
	v_pk_mul_f32 v[168:169], v[168:169], v[138:139] op_sel_hi:[1,0]
	v_pk_mul_f32 v[166:167], v[166:167], v[138:139] op_sel_hi:[1,0]
	s_waitcnt vmcnt(14)
	v_pk_fma_f32 v[58:59], v[58:59], v[168:169], v[62:63]
	v_pk_fma_f32 v[56:57], v[56:57], v[166:167], v[60:61]
	v_add_co_u32_e32 v120, vcc, s15, v120
	v_mov_b32_e32 v125, v128
	s_nop 0
	v_addc_co_u32_e32 v121, vcc, 0, v121, vcc
	v_mov_b32_e32 v131, v132
	v_pk_mul_f32 v[128:129], v[130:131], v[138:139] op_sel_hi:[1,0]
	v_pk_mul_f32 v[124:125], v[124:125], v[138:139] op_sel_hi:[1,0]
	v_pk_fma_f32 v[50:51], v[50:51], v[128:129], v[54:55]
	v_pk_fma_f32 v[48:49], v[48:49], v[124:125], v[52:53]
	v_mov_b32_e32 v123, v126
	v_mov_b32_e32 v85, v67
	v_mov_b32_e32 v105, v108
	v_mov_b32_e32 v107, v110
	v_mov_b32_e32 v87, v67
	v_mov_b32_e32 v113, v116
	v_mov_b32_e32 v89, v67
	v_mov_b32_e32 v91, v67
	v_mov_b32_e32 v93, v96
	v_mov_b32_e32 v95, v98
	global_load_dwordx4 v[170:173], v[162:163], off offset:16
	global_load_dwordx4 v[174:177], v[164:165], off offset:16
	global_load_dwordx4 v[178:181], v[162:163], off offset:2048
	global_load_dwordx4 v[182:185], v[164:165], off offset:2048
	global_load_dwordx4 v[186:189], v[162:163], off offset:2064
	global_load_dwordx4 v[190:193], v[164:165], off offset:2064
	v_lshl_add_u64 v[198:199], v[158:159], 0, v[84:85]
	global_load_dwordx4 v[194:197], v[198:199], off
	v_lshl_add_u64 v[204:205], v[160:161], 0, v[84:85]
	global_load_dwordx4 v[200:203], v[204:205], off
	v_lshl_add_u64 v[210:211], v[158:159], 0, v[86:87]
	global_load_dwordx4 v[206:209], v[210:211], off
	v_lshl_add_u64 v[216:217], v[160:161], 0, v[86:87]
	global_load_dwordx4 v[212:215], v[216:217], off
	v_lshl_add_u64 v[222:223], v[158:159], 0, v[88:89]
	global_load_dwordx4 v[218:221], v[222:223], off
	v_lshl_add_u64 v[228:229], v[160:161], 0, v[88:89]
	global_load_dwordx4 v[224:227], v[228:229], off
	v_lshl_add_u64 v[234:235], v[158:159], 0, v[90:91]
	global_load_dwordx4 v[230:233], v[234:235], off
	v_lshl_add_u64 v[240:241], v[160:161], 0, v[90:91]
	global_load_dwordx4 v[236:239], v[240:241], off
	v_add_u32_e32 v64, s14, v64
	v_cmp_lt_i32_e32 vcc, s22, v64
	v_lshl_add_u64 v[80:81], v[80:81], 0, s[16:17]
	s_or_b64 s[20:21], vcc, s[20:21]
	v_lshl_add_u64 v[82:83], v[82:83], 0, s[18:19]
	s_waitcnt vmcnt(15)
	v_pk_add_f32 v[60:61], v[152:153], 1.0 op_sel_hi:[1,0]
	v_pk_add_f32 v[62:63], v[150:151], 1.0 op_sel_hi:[1,0]
	s_waitcnt vmcnt(14)
	v_pk_fma_f32 v[58:59], v[58:59], v[60:61], v[156:157]
	v_pk_fma_f32 v[56:57], v[56:57], v[62:63], v[154:155]
	s_nop 0
	v_cvt_pk_bf16_f32 v56, v56, v57
	v_cvt_pk_bf16_f32 v57, v58, v59
	global_store_dwordx2 v[120:121], v[56:57], off
	s_nop 0
	s_waitcnt vmcnt(14)
	v_pk_add_f32 v[52:53], v[172:173], 1.0 op_sel_hi:[1,0]
	v_pk_add_f32 v[54:55], v[170:171], 1.0 op_sel_hi:[1,0]
	s_waitcnt vmcnt(13)
	v_pk_fma_f32 v[50:51], v[50:51], v[52:53], v[176:177]
	v_pk_fma_f32 v[48:49], v[48:49], v[54:55], v[174:175]
	v_pk_mul_f32 v[56:57], v[136:137], v[138:139] op_sel_hi:[1,0]
	v_cvt_pk_bf16_f32 v48, v48, v49
	v_cvt_pk_bf16_f32 v49, v50, v51
	global_store_dwordx2 v[120:121], v[48:49], off offset:8
	s_nop 0
	v_pk_mul_f32 v[58:59], v[122:123], v[138:139] op_sel_hi:[1,0]
	v_pk_fma_f32 v[42:43], v[42:43], v[56:57], v[46:47]
	v_pk_fma_f32 v[40:41], v[40:41], v[58:59], v[44:45]
	s_waitcnt vmcnt(13)
	v_pk_add_f32 v[44:45], v[180:181], 1.0 op_sel_hi:[1,0]
	v_pk_add_f32 v[46:47], v[178:179], 1.0 op_sel_hi:[1,0]
	s_waitcnt vmcnt(12)
	v_pk_fma_f32 v[42:43], v[42:43], v[44:45], v[184:185]
	v_pk_fma_f32 v[40:41], v[40:41], v[46:47], v[182:183]
	v_pk_mul_f32 v[48:49], v[118:119], v[138:139] op_sel_hi:[1,0]
	v_cvt_pk_bf16_f32 v40, v40, v41
	v_cvt_pk_bf16_f32 v41, v42, v43
	global_store_dwordx2 v[120:121], v[40:41], off offset:1024
	s_nop 0
	v_pk_mul_f32 v[50:51], v[114:115], v[138:139] op_sel_hi:[1,0]
	v_pk_fma_f32 v[34:35], v[34:35], v[48:49], v[38:39]
	v_pk_fma_f32 v[32:33], v[32:33], v[50:51], v[36:37]
	s_waitcnt vmcnt(12)
	v_pk_add_f32 v[38:39], v[188:189], 1.0 op_sel_hi:[1,0]
	v_pk_add_f32 v[40:41], v[186:187], 1.0 op_sel_hi:[1,0]
	s_waitcnt vmcnt(11)
	v_pk_fma_f32 v[34:35], v[34:35], v[38:39], v[192:193]
	v_pk_fma_f32 v[32:33], v[32:33], v[40:41], v[190:191]
	v_pk_mul_f32 v[40:41], v[106:107], v[138:139] op_sel_hi:[1,0]
	v_cvt_pk_bf16_f32 v32, v32, v33
	v_cvt_pk_bf16_f32 v33, v34, v35
	global_store_dwordx2 v[120:121], v[32:33], off offset:1032
	v_pk_mul_f32 v[42:43], v[104:105], v[138:139] op_sel_hi:[1,0]
	v_pk_fma_f32 v[26:27], v[26:27], v[40:41], v[30:31]
	v_pk_fma_f32 v[24:25], v[24:25], v[42:43], v[28:29]
	s_waitcnt vmcnt(11)
	v_pk_add_f32 v[30:31], v[196:197], 1.0 op_sel_hi:[1,0]
	v_pk_add_f32 v[32:33], v[194:195], 1.0 op_sel_hi:[1,0]
	s_waitcnt vmcnt(10)
	v_pk_fma_f32 v[26:27], v[26:27], v[30:31], v[202:203]
	v_pk_fma_f32 v[24:25], v[24:25], v[32:33], v[200:201]
	v_pk_mul_f32 v[32:33], v[134:135], v[138:139] op_sel_hi:[1,0]
	v_cvt_pk_bf16_f32 v24, v24, v25
	v_cvt_pk_bf16_f32 v25, v26, v27
	global_store_dwordx2 v[120:121], v[24:25], off offset:2048
	v_pk_mul_f32 v[34:35], v[112:113], v[138:139] op_sel_hi:[1,0]
	v_pk_fma_f32 v[18:19], v[18:19], v[32:33], v[22:23]
	v_pk_fma_f32 v[16:17], v[16:17], v[34:35], v[20:21]
	s_waitcnt vmcnt(10)
	v_pk_add_f32 v[22:23], v[208:209], 1.0 op_sel_hi:[1,0]
	v_pk_add_f32 v[24:25], v[206:207], 1.0 op_sel_hi:[1,0]
	s_waitcnt vmcnt(9)
	v_pk_fma_f32 v[18:19], v[18:19], v[22:23], v[214:215]
	v_pk_fma_f32 v[16:17], v[16:17], v[24:25], v[212:213]
	v_pk_mul_f32 v[24:25], v[102:103], v[138:139] op_sel_hi:[1,0]
	v_cvt_pk_bf16_f32 v16, v16, v17
	v_cvt_pk_bf16_f32 v17, v18, v19
	global_store_dwordx2 v[120:121], v[16:17], off offset:2056
	v_pk_mul_f32 v[26:27], v[100:101], v[138:139] op_sel_hi:[1,0]
	v_pk_fma_f32 v[10:11], v[10:11], v[24:25], v[14:15]
	v_pk_fma_f32 v[8:9], v[8:9], v[26:27], v[12:13]
	s_waitcnt vmcnt(9)
	v_pk_add_f32 v[14:15], v[220:221], 1.0 op_sel_hi:[1,0]
	v_pk_add_f32 v[16:17], v[218:219], 1.0 op_sel_hi:[1,0]
	s_waitcnt vmcnt(8)
	v_pk_fma_f32 v[10:11], v[10:11], v[14:15], v[226:227]
	v_pk_fma_f32 v[8:9], v[8:9], v[16:17], v[224:225]
	v_pk_mul_f32 v[16:17], v[94:95], v[138:139] op_sel_hi:[1,0]
	v_cvt_pk_bf16_f32 v8, v8, v9
	v_cvt_pk_bf16_f32 v9, v10, v11
	global_store_dwordx2 v[120:121], v[8:9], off offset:3072
	v_pk_mul_f32 v[18:19], v[92:93], v[138:139] op_sel_hi:[1,0]
	v_pk_fma_f32 v[2:3], v[2:3], v[16:17], v[6:7]
	v_pk_fma_f32 v[0:1], v[0:1], v[18:19], v[4:5]
	s_waitcnt vmcnt(8)
	v_pk_add_f32 v[4:5], v[232:233], 1.0 op_sel_hi:[1,0]
	v_pk_add_f32 v[6:7], v[230:231], 1.0 op_sel_hi:[1,0]
	s_waitcnt vmcnt(7)
	v_pk_fma_f32 v[2:3], v[2:3], v[4:5], v[238:239]
	v_pk_fma_f32 v[0:1], v[0:1], v[6:7], v[236:237]
	s_nop 0
	v_cvt_pk_bf16_f32 v0, v0, v1
	v_cvt_pk_bf16_f32 v1, v2, v3
	global_store_dwordx2 v[120:121], v[0:1], off offset:3080
	s_andn2_b64 exec, exec, s[20:21]
	s_cbranch_execz .LBB0_750

.LBB0_946:
	s_or_b64 exec, exec, s[4:5]
	v_ashrrev_i32_e32 v89, 13, v64
	v_mul_i32_i24_e32 v154, 6, v89
	v_ashrrev_i32_e32 v155, 31, v154
	v_lshlrev_b64 v[154:155], 13, v[154:155]
	v_lshl_add_u64 v[162:163], s[10:11], 0, v[154:155]
	v_lshl_add_u64 v[164:165], s[12:13], 0, v[154:155]
	v_lshl_add_u64 v[166:167], v[162:163], 0, v[66:67]
	global_load_dwordx4 v[154:157], v[166:167], off
	v_lshl_add_u64 v[168:169], v[164:165], 0, v[66:67]
	global_load_dwordx4 v[158:161], v[168:169], off
	v_mov_b32_e32 v170, v129
	v_mov_b32_e32 v171, v133
	v_mov_b32_e32 v172, v135
	v_mov_b32_e32 v173, v137
	v_pk_mul_f32 v[172:173], v[172:173], v[142:143] op_sel_hi:[1,0]
	v_pk_mul_f32 v[170:171], v[170:171], v[142:143] op_sel_hi:[1,0]
	s_waitcnt vmcnt(14)
	v_pk_fma_f32 v[58:59], v[58:59], v[172:173], v[62:63]
	v_pk_fma_f32 v[56:57], v[56:57], v[170:171], v[60:61]
	v_add_co_u32_e32 v124, vcc, s15, v124
	v_mov_b32_e32 v129, v132
	s_nop 0
	v_addc_co_u32_e32 v125, vcc, 0, v125, vcc
	v_mov_b32_e32 v135, v136
	v_pk_mul_f32 v[132:133], v[134:135], v[142:143] op_sel_hi:[1,0]
	v_pk_mul_f32 v[128:129], v[128:129], v[142:143] op_sel_hi:[1,0]
	v_pk_fma_f32 v[50:51], v[50:51], v[132:133], v[54:55]
	v_pk_fma_f32 v[48:49], v[48:49], v[128:129], v[52:53]
	v_mov_b32_e32 v127, v130
	v_mov_b32_e32 v89, v67
	v_mov_b32_e32 v109, v112
	v_mov_b32_e32 v111, v114
	v_mov_b32_e32 v91, v67
	v_mov_b32_e32 v117, v120
	v_mov_b32_e32 v93, v67
	v_mov_b32_e32 v95, v67
	v_mov_b32_e32 v97, v100
	v_mov_b32_e32 v99, v102
	global_load_dwordx4 v[174:177], v[166:167], off offset:16
	global_load_dwordx4 v[178:181], v[168:169], off offset:16
	global_load_dwordx4 v[182:185], v[166:167], off offset:2048
	global_load_dwordx4 v[186:189], v[168:169], off offset:2048
	global_load_dwordx4 v[190:193], v[166:167], off offset:2064
	global_load_dwordx4 v[194:197], v[168:169], off offset:2064
	v_lshl_add_u64 v[202:203], v[162:163], 0, v[88:89]
	global_load_dwordx4 v[198:201], v[202:203], off
	v_lshl_add_u64 v[208:209], v[164:165], 0, v[88:89]
	global_load_dwordx4 v[204:207], v[208:209], off
	v_lshl_add_u64 v[214:215], v[162:163], 0, v[90:91]
	global_load_dwordx4 v[210:213], v[214:215], off
	v_lshl_add_u64 v[220:221], v[164:165], 0, v[90:91]
	global_load_dwordx4 v[216:219], v[220:221], off
	v_lshl_add_u64 v[226:227], v[162:163], 0, v[92:93]
	global_load_dwordx4 v[222:225], v[226:227], off
	v_lshl_add_u64 v[232:233], v[164:165], 0, v[92:93]
	global_load_dwordx4 v[228:231], v[232:233], off
	v_lshl_add_u64 v[238:239], v[162:163], 0, v[94:95]
	global_load_dwordx4 v[234:237], v[238:239], off
	v_lshl_add_u64 v[244:245], v[164:165], 0, v[94:95]
	global_load_dwordx4 v[240:243], v[244:245], off
	v_add_u32_e32 v64, s14, v64
	v_cmp_lt_i32_e32 vcc, s22, v64
	v_lshl_add_u64 v[84:85], v[84:85], 0, s[16:17]
	s_or_b64 s[20:21], vcc, s[20:21]
	v_lshl_add_u64 v[86:87], v[86:87], 0, s[18:19]
	s_waitcnt vmcnt(15)
	v_pk_add_f32 v[60:61], v[156:157], 1.0 op_sel_hi:[1,0]
	v_pk_add_f32 v[62:63], v[154:155], 1.0 op_sel_hi:[1,0]
	s_waitcnt vmcnt(14)
	v_pk_fma_f32 v[58:59], v[58:59], v[60:61], v[160:161]
	v_pk_fma_f32 v[56:57], v[56:57], v[62:63], v[158:159]
	s_nop 0
	v_cvt_pk_bf16_f32 v56, v56, v57
	v_cvt_pk_bf16_f32 v57, v58, v59
	global_store_dwordx2 v[124:125], v[56:57], off
	s_nop 0
	s_waitcnt vmcnt(14)
	v_pk_add_f32 v[52:53], v[176:177], 1.0 op_sel_hi:[1,0]
	v_pk_add_f32 v[54:55], v[174:175], 1.0 op_sel_hi:[1,0]
	s_waitcnt vmcnt(13)
	v_pk_fma_f32 v[50:51], v[50:51], v[52:53], v[180:181]
	v_pk_fma_f32 v[48:49], v[48:49], v[54:55], v[178:179]
	v_pk_mul_f32 v[56:57], v[140:141], v[142:143] op_sel_hi:[1,0]
	v_cvt_pk_bf16_f32 v48, v48, v49
	v_cvt_pk_bf16_f32 v49, v50, v51
	global_store_dwordx2 v[124:125], v[48:49], off offset:8
	s_nop 0
	v_pk_mul_f32 v[58:59], v[126:127], v[142:143] op_sel_hi:[1,0]
	v_pk_fma_f32 v[42:43], v[42:43], v[56:57], v[46:47]
	v_pk_fma_f32 v[40:41], v[40:41], v[58:59], v[44:45]
	s_waitcnt vmcnt(13)
	v_pk_add_f32 v[44:45], v[184:185], 1.0 op_sel_hi:[1,0]
	v_pk_add_f32 v[46:47], v[182:183], 1.0 op_sel_hi:[1,0]
	s_waitcnt vmcnt(12)
	v_pk_fma_f32 v[42:43], v[42:43], v[44:45], v[188:189]
	v_pk_fma_f32 v[40:41], v[40:41], v[46:47], v[186:187]
	v_pk_mul_f32 v[48:49], v[122:123], v[142:143] op_sel_hi:[1,0]
	v_cvt_pk_bf16_f32 v40, v40, v41
	v_cvt_pk_bf16_f32 v41, v42, v43
	global_store_dwordx2 v[124:125], v[40:41], off offset:1024
	s_nop 0
	v_pk_mul_f32 v[50:51], v[118:119], v[142:143] op_sel_hi:[1,0]
	v_pk_fma_f32 v[34:35], v[34:35], v[48:49], v[38:39]
	v_pk_fma_f32 v[32:33], v[32:33], v[50:51], v[36:37]
	s_waitcnt vmcnt(12)
	v_pk_add_f32 v[38:39], v[192:193], 1.0 op_sel_hi:[1,0]
	v_pk_add_f32 v[40:41], v[190:191], 1.0 op_sel_hi:[1,0]
	s_waitcnt vmcnt(11)
	v_pk_fma_f32 v[34:35], v[34:35], v[38:39], v[196:197]
	v_pk_fma_f32 v[32:33], v[32:33], v[40:41], v[194:195]
	v_pk_mul_f32 v[40:41], v[110:111], v[142:143] op_sel_hi:[1,0]
	v_cvt_pk_bf16_f32 v32, v32, v33
	v_cvt_pk_bf16_f32 v33, v34, v35
	global_store_dwordx2 v[124:125], v[32:33], off offset:1032
	v_pk_mul_f32 v[42:43], v[108:109], v[142:143] op_sel_hi:[1,0]
	v_pk_fma_f32 v[26:27], v[26:27], v[40:41], v[30:31]
	v_pk_fma_f32 v[24:25], v[24:25], v[42:43], v[28:29]
	s_waitcnt vmcnt(11)
	v_pk_add_f32 v[30:31], v[200:201], 1.0 op_sel_hi:[1,0]
	v_pk_add_f32 v[32:33], v[198:199], 1.0 op_sel_hi:[1,0]
	s_waitcnt vmcnt(10)
	v_pk_fma_f32 v[26:27], v[26:27], v[30:31], v[206:207]
	v_pk_fma_f32 v[24:25], v[24:25], v[32:33], v[204:205]
	v_pk_mul_f32 v[32:33], v[138:139], v[142:143] op_sel_hi:[1,0]
	v_cvt_pk_bf16_f32 v24, v24, v25
	v_cvt_pk_bf16_f32 v25, v26, v27
	global_store_dwordx2 v[124:125], v[24:25], off offset:2048
	v_pk_mul_f32 v[34:35], v[116:117], v[142:143] op_sel_hi:[1,0]
	v_pk_fma_f32 v[18:19], v[18:19], v[32:33], v[22:23]
	v_pk_fma_f32 v[16:17], v[16:17], v[34:35], v[20:21]
	s_waitcnt vmcnt(10)
	v_pk_add_f32 v[22:23], v[212:213], 1.0 op_sel_hi:[1,0]
	v_pk_add_f32 v[24:25], v[210:211], 1.0 op_sel_hi:[1,0]
	s_waitcnt vmcnt(9)
	v_pk_fma_f32 v[18:19], v[18:19], v[22:23], v[218:219]
	v_pk_fma_f32 v[16:17], v[16:17], v[24:25], v[216:217]
	v_pk_mul_f32 v[24:25], v[106:107], v[142:143] op_sel_hi:[1,0]
	v_cvt_pk_bf16_f32 v16, v16, v17
	v_cvt_pk_bf16_f32 v17, v18, v19
	global_store_dwordx2 v[124:125], v[16:17], off offset:2056
	v_pk_mul_f32 v[26:27], v[104:105], v[142:143] op_sel_hi:[1,0]
	v_pk_fma_f32 v[10:11], v[10:11], v[24:25], v[14:15]
	v_pk_fma_f32 v[8:9], v[8:9], v[26:27], v[12:13]
	s_waitcnt vmcnt(9)
	v_pk_add_f32 v[14:15], v[224:225], 1.0 op_sel_hi:[1,0]
	v_pk_add_f32 v[16:17], v[222:223], 1.0 op_sel_hi:[1,0]
	s_waitcnt vmcnt(8)
	v_pk_fma_f32 v[10:11], v[10:11], v[14:15], v[230:231]
	v_pk_fma_f32 v[8:9], v[8:9], v[16:17], v[228:229]
	v_pk_mul_f32 v[16:17], v[98:99], v[142:143] op_sel_hi:[1,0]
	v_cvt_pk_bf16_f32 v8, v8, v9
	v_cvt_pk_bf16_f32 v9, v10, v11
	global_store_dwordx2 v[124:125], v[8:9], off offset:3072
	v_pk_mul_f32 v[18:19], v[96:97], v[142:143] op_sel_hi:[1,0]
	v_pk_fma_f32 v[2:3], v[2:3], v[16:17], v[6:7]
	v_pk_fma_f32 v[0:1], v[0:1], v[18:19], v[4:5]
	s_waitcnt vmcnt(8)
	v_pk_add_f32 v[4:5], v[236:237], 1.0 op_sel_hi:[1,0]
	v_pk_add_f32 v[6:7], v[234:235], 1.0 op_sel_hi:[1,0]
	s_waitcnt vmcnt(7)
	v_pk_fma_f32 v[2:3], v[2:3], v[4:5], v[242:243]
	v_pk_fma_f32 v[0:1], v[0:1], v[6:7], v[240:241]
	s_nop 0
	v_cvt_pk_bf16_f32 v0, v0, v1
	v_cvt_pk_bf16_f32 v1, v2, v3
	global_store_dwordx2 v[124:125], v[0:1], off offset:3080
	s_andn2_b64 exec, exec, s[20:21]
	s_cbranch_execz .LBB0_949

.Lsel_start:
	s_mov_b64 exec, -1
	v_mbcnt_lo_u32_b32 v131, -1, 0
	v_mbcnt_hi_u32_b32 v131, -1, v131
	v_lshlrev_b32_e32 v133, 2, v131
	v_mov_b32_e32 v135, 1
	v_readfirstlane_b32 s16, v146
	s_lshr_b32 s16, s16, 6
	s_lshl_b32 s93, s16, 13
	s_add_i32 s93, s93, 73728
	v_mov_b32_e32 v136, s93
	s_lshl_b32 s93, s16, 8
	s_add_i32 s93, s93, 139264
	v_add_u32_e32 v137, s93, v133
	s_movk_i32 s95, 0x1ffc
	s_ashr_i32 s17, s63, 9
	s_and_b32 s93, s63, 0x1ff
	s_sub_i32 s94, 0x2ff, s93
	s_cmpk_lt_u32 s93, 0x100
	s_cselect_b32 s93, s93, s94
	s_lshl_b32 s18, s93, 4
	s_mov_b32 s19, 0

.Lsel_pass:
	v_mov_b32_e32 v240, 0
	v_mov_b32_e32 v241, 0
	v_mov_b32_e32 v242, 0
	v_mov_b32_e32 v243, 0
	v_lshl_add_u32 v140, v131, 4, v136
	ds_write_b128 v140, v[240:243]
	ds_write_b128 v140, v[240:243] offset:1024
	ds_write_b128 v140, v[240:243] offset:2048
	ds_write_b128 v140, v[240:243] offset:3072
	ds_write_b128 v140, v[240:243] offset:4096
	ds_write_b128 v140, v[240:243] offset:5120
	ds_write_b128 v140, v[240:243] offset:6144
	ds_write_b128 v140, v[240:243] offset:7168
	s_waitcnt lgkmcnt(0)
	s_cmp_lg_u32 s88, 0
	s_cbranch_scc1 .Lsel_histm
	v_lshrrev_b32_e32 v240, 19, v0
	v_and_or_b32 v240, v240, s95, v136
	ds_add_u32 v240, v135
	v_lshrrev_b32_e32 v241, 19, v1
	v_and_or_b32 v241, v241, s95, v136
	ds_add_u32 v241, v135
	v_lshrrev_b32_e32 v242, 19, v2
	v_and_or_b32 v242, v242, s95, v136
	ds_add_u32 v242, v135
	v_lshrrev_b32_e32 v243, 19, v3
	v_and_or_b32 v243, v243, s95, v136
	ds_add_u32 v243, v135
	v_lshrrev_b32_e32 v244, 19, v4
	v_and_or_b32 v244, v244, s95, v136
	ds_add_u32 v244, v135
	v_lshrrev_b32_e32 v245, 19, v5
	v_and_or_b32 v245, v245, s95, v136
	ds_add_u32 v245, v135
	v_lshrrev_b32_e32 v246, 19, v6
	v_and_or_b32 v246, v246, s95, v136
	ds_add_u32 v246, v135
	v_lshrrev_b32_e32 v247, 19, v7
	v_and_or_b32 v247, v247, s95, v136
	ds_add_u32 v247, v135
	v_lshrrev_b32_e32 v240, 19, v8
	v_and_or_b32 v240, v240, s95, v136
	ds_add_u32 v240, v135
	v_lshrrev_b32_e32 v241, 19, v9
	v_and_or_b32 v241, v241, s95, v136
	ds_add_u32 v241, v135
	v_lshrrev_b32_e32 v242, 19, v10
	v_and_or_b32 v242, v242, s95, v136
	ds_add_u32 v242, v135
	v_lshrrev_b32_e32 v243, 19, v11
	v_and_or_b32 v243, v243, s95, v136
	ds_add_u32 v243, v135
	v_lshrrev_b32_e32 v244, 19, v12
	v_and_or_b32 v244, v244, s95, v136
	ds_add_u32 v244, v135
	v_lshrrev_b32_e32 v245, 19, v13
	v_and_or_b32 v245, v245, s95, v136
	ds_add_u32 v245, v135
	v_lshrrev_b32_e32 v246, 19, v14
	v_and_or_b32 v246, v246, s95, v136
	ds_add_u32 v246, v135
	v_lshrrev_b32_e32 v247, 19, v15
	v_and_or_b32 v247, v247, s95, v136
	ds_add_u32 v247, v135
	s_cmpk_le_u32 s34, 16
	s_cbranch_scc1 .Lsel_hist_done
	v_lshrrev_b32_e32 v240, 19, v16
	v_and_or_b32 v240, v240, s95, v136
	ds_add_u32 v240, v135
	v_lshrrev_b32_e32 v241, 19, v17
	v_and_or_b32 v241, v241, s95, v136
	ds_add_u32 v241, v135
	v_lshrrev_b32_e32 v242, 19, v18
	v_and_or_b32 v242, v242, s95, v136
	ds_add_u32 v242, v135
	v_lshrrev_b32_e32 v243, 19, v19
	v_and_or_b32 v243, v243, s95, v136
	ds_add_u32 v243, v135
	v_lshrrev_b32_e32 v244, 19, v20
	v_and_or_b32 v244, v244, s95, v136
	ds_add_u32 v244, v135
	v_lshrrev_b32_e32 v245, 19, v21
	v_and_or_b32 v245, v245, s95, v136
	ds_add_u32 v245, v135
	v_lshrrev_b32_e32 v246, 19, v22
	v_and_or_b32 v246, v246, s95, v136
	ds_add_u32 v246, v135
	v_lshrrev_b32_e32 v247, 19, v23
	v_and_or_b32 v247, v247, s95, v136
	ds_add_u32 v247, v135
	v_lshrrev_b32_e32 v240, 19, v24
	v_and_or_b32 v240, v240, s95, v136
	ds_add_u32 v240, v135
	v_lshrrev_b32_e32 v241, 19, v25
	v_and_or_b32 v241, v241, s95, v136
	ds_add_u32 v241, v135
	v_lshrrev_b32_e32 v242, 19, v26
	v_and_or_b32 v242, v242, s95, v136
	ds_add_u32 v242, v135
	v_lshrrev_b32_e32 v243, 19, v27
	v_and_or_b32 v243, v243, s95, v136
	ds_add_u32 v243, v135
	v_lshrrev_b32_e32 v244, 19, v28
	v_and_or_b32 v244, v244, s95, v136
	ds_add_u32 v244, v135
	v_lshrrev_b32_e32 v245, 19, v29
	v_and_or_b32 v245, v245, s95, v136
	ds_add_u32 v245, v135
	v_lshrrev_b32_e32 v246, 19, v30
	v_and_or_b32 v246, v246, s95, v136
	ds_add_u32 v246, v135
	v_lshrrev_b32_e32 v247, 19, v31
	v_and_or_b32 v247, v247, s95, v136
	ds_add_u32 v247, v135
	s_cmpk_le_u32 s34, 32
	s_cbranch_scc1 .Lsel_hist_done
	v_lshrrev_b32_e32 v240, 19, v32
	v_and_or_b32 v240, v240, s95, v136
	ds_add_u32 v240, v135
	v_lshrrev_b32_e32 v241, 19, v33
	v_and_or_b32 v241, v241, s95, v136
	ds_add_u32 v241, v135
	v_lshrrev_b32_e32 v242, 19, v34
	v_and_or_b32 v242, v242, s95, v136
	ds_add_u32 v242, v135
	v_lshrrev_b32_e32 v243, 19, v35
	v_and_or_b32 v243, v243, s95, v136
	ds_add_u32 v243, v135
	v_lshrrev_b32_e32 v244, 19, v36
	v_and_or_b32 v244, v244, s95, v136
	ds_add_u32 v244, v135
	v_lshrrev_b32_e32 v245, 19, v37
	v_and_or_b32 v245, v245, s95, v136
	ds_add_u32 v245, v135
	v_lshrrev_b32_e32 v246, 19, v38
	v_and_or_b32 v246, v246, s95, v136
	ds_add_u32 v246, v135
	v_lshrrev_b32_e32 v247, 19, v39
	v_and_or_b32 v247, v247, s95, v136
	ds_add_u32 v247, v135
	v_lshrrev_b32_e32 v240, 19, v40
	v_and_or_b32 v240, v240, s95, v136
	ds_add_u32 v240, v135
	v_lshrrev_b32_e32 v241, 19, v41
	v_and_or_b32 v241, v241, s95, v136
	ds_add_u32 v241, v135
	v_lshrrev_b32_e32 v242, 19, v42
	v_and_or_b32 v242, v242, s95, v136
	ds_add_u32 v242, v135
	v_lshrrev_b32_e32 v243, 19, v43
	v_and_or_b32 v243, v243, s95, v136
	ds_add_u32 v243, v135
	v_lshrrev_b32_e32 v244, 19, v44
	v_and_or_b32 v244, v244, s95, v136
	ds_add_u32 v244, v135
	v_lshrrev_b32_e32 v245, 19, v45
	v_and_or_b32 v245, v245, s95, v136
	ds_add_u32 v245, v135
	v_lshrrev_b32_e32 v246, 19, v46
	v_and_or_b32 v246, v246, s95, v136
	ds_add_u32 v246, v135
	v_lshrrev_b32_e32 v247, 19, v47
	v_and_or_b32 v247, v247, s95, v136
	ds_add_u32 v247, v135
	s_cmpk_le_u32 s34, 48
	s_cbranch_scc1 .Lsel_hist_done
	v_lshrrev_b32_e32 v240, 19, v48
	v_and_or_b32 v240, v240, s95, v136
	ds_add_u32 v240, v135
	v_lshrrev_b32_e32 v241, 19, v49
	v_and_or_b32 v241, v241, s95, v136
	ds_add_u32 v241, v135
	v_lshrrev_b32_e32 v242, 19, v50
	v_and_or_b32 v242, v242, s95, v136
	ds_add_u32 v242, v135
	v_lshrrev_b32_e32 v243, 19, v51
	v_and_or_b32 v243, v243, s95, v136
	ds_add_u32 v243, v135
	v_lshrrev_b32_e32 v244, 19, v52
	v_and_or_b32 v244, v244, s95, v136
	ds_add_u32 v244, v135
	v_lshrrev_b32_e32 v245, 19, v53
	v_and_or_b32 v245, v245, s95, v136
	ds_add_u32 v245, v135
	v_lshrrev_b32_e32 v246, 19, v54
	v_and_or_b32 v246, v246, s95, v136
	ds_add_u32 v246, v135
	v_lshrrev_b32_e32 v247, 19, v55
	v_and_or_b32 v247, v247, s95, v136
	ds_add_u32 v247, v135
	v_lshrrev_b32_e32 v240, 19, v56
	v_and_or_b32 v240, v240, s95, v136
	ds_add_u32 v240, v135
	v_lshrrev_b32_e32 v241, 19, v57
	v_and_or_b32 v241, v241, s95, v136
	ds_add_u32 v241, v135
	v_lshrrev_b32_e32 v242, 19, v58
	v_and_or_b32 v242, v242, s95, v136
	ds_add_u32 v242, v135
	v_lshrrev_b32_e32 v243, 19, v59
	v_and_or_b32 v243, v243, s95, v136
	ds_add_u32 v243, v135
	v_lshrrev_b32_e32 v244, 19, v60
	v_and_or_b32 v244, v244, s95, v136
	ds_add_u32 v244, v135
	v_lshrrev_b32_e32 v245, 19, v61
	v_and_or_b32 v245, v245, s95, v136
	ds_add_u32 v245, v135
	v_lshrrev_b32_e32 v246, 19, v62
	v_and_or_b32 v246, v246, s95, v136
	ds_add_u32 v246, v135
	v_lshrrev_b32_e32 v247, 19, v63
	v_and_or_b32 v247, v247, s95, v136
	ds_add_u32 v247, v135
	s_cmpk_le_u32 s34, 64
	s_cbranch_scc1 .Lsel_hist_done
	v_lshrrev_b32_e32 v240, 19, v64
	v_and_or_b32 v240, v240, s95, v136
	ds_add_u32 v240, v135
	v_lshrrev_b32_e32 v241, 19, v65
	v_and_or_b32 v241, v241, s95, v136
	ds_add_u32 v241, v135
	v_lshrrev_b32_e32 v242, 19, v66
	v_and_or_b32 v242, v242, s95, v136
	ds_add_u32 v242, v135
	v_lshrrev_b32_e32 v243, 19, v67
	v_and_or_b32 v243, v243, s95, v136
	ds_add_u32 v243, v135
	v_lshrrev_b32_e32 v244, 19, v68
	v_and_or_b32 v244, v244, s95, v136
	ds_add_u32 v244, v135
	v_lshrrev_b32_e32 v245, 19, v69
	v_and_or_b32 v245, v245, s95, v136
	ds_add_u32 v245, v135
	v_lshrrev_b32_e32 v246, 19, v70
	v_and_or_b32 v246, v246, s95, v136
	ds_add_u32 v246, v135
	v_lshrrev_b32_e32 v247, 19, v71
	v_and_or_b32 v247, v247, s95, v136
	ds_add_u32 v247, v135
	v_lshrrev_b32_e32 v240, 19, v72
	v_and_or_b32 v240, v240, s95, v136
	ds_add_u32 v240, v135
	v_lshrrev_b32_e32 v241, 19, v73
	v_and_or_b32 v241, v241, s95, v136
	ds_add_u32 v241, v135
	v_lshrrev_b32_e32 v242, 19, v74
	v_and_or_b32 v242, v242, s95, v136
	ds_add_u32 v242, v135
	v_lshrrev_b32_e32 v243, 19, v75
	v_and_or_b32 v243, v243, s95, v136
	ds_add_u32 v243, v135
	v_lshrrev_b32_e32 v244, 19, v76
	v_and_or_b32 v244, v244, s95, v136
	ds_add_u32 v244, v135
	v_lshrrev_b32_e32 v245, 19, v77
	v_and_or_b32 v245, v245, s95, v136
	ds_add_u32 v245, v135
	v_lshrrev_b32_e32 v246, 19, v78
	v_and_or_b32 v246, v246, s95, v136
	ds_add_u32 v246, v135
	v_lshrrev_b32_e32 v247, 19, v79
	v_and_or_b32 v247, v247, s95, v136
	ds_add_u32 v247, v135
	s_cmpk_le_u32 s34, 80
	s_cbranch_scc1 .Lsel_hist_done
	v_lshrrev_b32_e32 v240, 19, v80
	v_and_or_b32 v240, v240, s95, v136
	ds_add_u32 v240, v135
	v_lshrrev_b32_e32 v241, 19, v81
	v_and_or_b32 v241, v241, s95, v136
	ds_add_u32 v241, v135
	v_lshrrev_b32_e32 v242, 19, v82
	v_and_or_b32 v242, v242, s95, v136
	ds_add_u32 v242, v135
	v_lshrrev_b32_e32 v243, 19, v83
	v_and_or_b32 v243, v243, s95, v136
	ds_add_u32 v243, v135
	v_lshrrev_b32_e32 v244, 19, v84
	v_and_or_b32 v244, v244, s95, v136
	ds_add_u32 v244, v135
	v_lshrrev_b32_e32 v245, 19, v85
	v_and_or_b32 v245, v245, s95, v136
	ds_add_u32 v245, v135
	v_lshrrev_b32_e32 v246, 19, v86
	v_and_or_b32 v246, v246, s95, v136
	ds_add_u32 v246, v135
	v_lshrrev_b32_e32 v247, 19, v87
	v_and_or_b32 v247, v247, s95, v136
	ds_add_u32 v247, v135
	v_lshrrev_b32_e32 v240, 19, v88
	v_and_or_b32 v240, v240, s95, v136
	ds_add_u32 v240, v135
	v_lshrrev_b32_e32 v241, 19, v89
	v_and_or_b32 v241, v241, s95, v136
	ds_add_u32 v241, v135
	v_lshrrev_b32_e32 v242, 19, v90
	v_and_or_b32 v242, v242, s95, v136
	ds_add_u32 v242, v135
	v_lshrrev_b32_e32 v243, 19, v91
	v_and_or_b32 v243, v243, s95, v136
	ds_add_u32 v243, v135
	v_lshrrev_b32_e32 v244, 19, v92
	v_and_or_b32 v244, v244, s95, v136
	ds_add_u32 v244, v135
	v_lshrrev_b32_e32 v245, 19, v93
	v_and_or_b32 v245, v245, s95, v136
	ds_add_u32 v245, v135
	v_lshrrev_b32_e32 v246, 19, v94
	v_and_or_b32 v246, v246, s95, v136
	ds_add_u32 v246, v135
	v_lshrrev_b32_e32 v247, 19, v95
	v_and_or_b32 v247, v247, s95, v136
	ds_add_u32 v247, v135
	s_cmpk_le_u32 s34, 96
	s_cbranch_scc1 .Lsel_hist_done
	v_lshrrev_b32_e32 v240, 19, v208
	v_and_or_b32 v240, v240, s95, v136
	ds_add_u32 v240, v135
	v_lshrrev_b32_e32 v241, 19, v209
	v_and_or_b32 v241, v241, s95, v136
	ds_add_u32 v241, v135
	v_lshrrev_b32_e32 v242, 19, v210
	v_and_or_b32 v242, v242, s95, v136
	ds_add_u32 v242, v135
	v_lshrrev_b32_e32 v243, 19, v211
	v_and_or_b32 v243, v243, s95, v136
	ds_add_u32 v243, v135
	v_lshrrev_b32_e32 v244, 19, v212
	v_and_or_b32 v244, v244, s95, v136
	ds_add_u32 v244, v135
	v_lshrrev_b32_e32 v245, 19, v213
	v_and_or_b32 v245, v245, s95, v136
	ds_add_u32 v245, v135
	v_lshrrev_b32_e32 v246, 19, v214
	v_and_or_b32 v246, v246, s95, v136
	ds_add_u32 v246, v135
	v_lshrrev_b32_e32 v247, 19, v215
	v_and_or_b32 v247, v247, s95, v136
	ds_add_u32 v247, v135
	v_lshrrev_b32_e32 v240, 19, v216
	v_and_or_b32 v240, v240, s95, v136
	ds_add_u32 v240, v135
	v_lshrrev_b32_e32 v241, 19, v217
	v_and_or_b32 v241, v241, s95, v136
	ds_add_u32 v241, v135
	v_lshrrev_b32_e32 v242, 19, v218
	v_and_or_b32 v242, v242, s95, v136
	ds_add_u32 v242, v135
	v_lshrrev_b32_e32 v243, 19, v219
	v_and_or_b32 v243, v243, s95, v136
	ds_add_u32 v243, v135
	v_lshrrev_b32_e32 v244, 19, v220
	v_and_or_b32 v244, v244, s95, v136
	ds_add_u32 v244, v135
	v_lshrrev_b32_e32 v245, 19, v221
	v_and_or_b32 v245, v245, s95, v136
	ds_add_u32 v245, v135
	v_lshrrev_b32_e32 v246, 19, v222
	v_and_or_b32 v246, v246, s95, v136
	ds_add_u32 v246, v135
	v_lshrrev_b32_e32 v247, 19, v223
	v_and_or_b32 v247, v247, s95, v136
	ds_add_u32 v247, v135
	s_cmpk_le_u32 s34, 112
	s_cbranch_scc1 .Lsel_hist_done
	v_lshrrev_b32_e32 v240, 19, v224
	v_and_or_b32 v240, v240, s95, v136
	ds_add_u32 v240, v135
	v_lshrrev_b32_e32 v241, 19, v225
	v_and_or_b32 v241, v241, s95, v136
	ds_add_u32 v241, v135
	v_lshrrev_b32_e32 v242, 19, v226
	v_and_or_b32 v242, v242, s95, v136
	ds_add_u32 v242, v135
	v_lshrrev_b32_e32 v243, 19, v227
	v_and_or_b32 v243, v243, s95, v136
	ds_add_u32 v243, v135
	v_lshrrev_b32_e32 v244, 19, v228
	v_and_or_b32 v244, v244, s95, v136
	ds_add_u32 v244, v135
	v_lshrrev_b32_e32 v245, 19, v229
	v_and_or_b32 v245, v245, s95, v136
	ds_add_u32 v245, v135
	v_lshrrev_b32_e32 v246, 19, v230
	v_and_or_b32 v246, v246, s95, v136
	ds_add_u32 v246, v135
	v_lshrrev_b32_e32 v247, 19, v231
	v_and_or_b32 v247, v247, s95, v136
	ds_add_u32 v247, v135
	v_lshrrev_b32_e32 v240, 19, v232
	v_and_or_b32 v240, v240, s95, v136
	ds_add_u32 v240, v135
	v_lshrrev_b32_e32 v241, 19, v233
	v_and_or_b32 v241, v241, s95, v136
	ds_add_u32 v241, v135
	v_lshrrev_b32_e32 v242, 19, v234
	v_and_or_b32 v242, v242, s95, v136
	ds_add_u32 v242, v135
	v_lshrrev_b32_e32 v243, 19, v235
	v_and_or_b32 v243, v243, s95, v136
	ds_add_u32 v243, v135
	v_lshrrev_b32_e32 v244, 19, v236
	v_and_or_b32 v244, v244, s95, v136
	ds_add_u32 v244, v135
	v_lshrrev_b32_e32 v245, 19, v237
	v_and_or_b32 v245, v245, s95, v136
	ds_add_u32 v245, v135
	v_lshrrev_b32_e32 v246, 19, v238
	v_and_or_b32 v246, v246, s95, v136
	ds_add_u32 v246, v135
	v_lshrrev_b32_e32 v247, 19, v239
	v_and_or_b32 v247, v247, s95, v136
	ds_add_u32 v247, v135
	s_branch .Lsel_hist_done
.Lsel_histm:
	v_xor_b32_e32 v240, s57, v0
	v_cmpx_gt_u32_e32 vcc, s86, v240
	v_lshrrev_b32_e32 v241, s87, v240
	v_lshl_add_u32 v241, v241, 2, v136
	ds_add_u32 v241, v135
	s_mov_b64 exec, -1
	v_xor_b32_e32 v242, s57, v1
	v_cmpx_gt_u32_e32 vcc, s86, v242
	v_lshrrev_b32_e32 v243, s87, v242
	v_lshl_add_u32 v243, v243, 2, v136
	ds_add_u32 v243, v135
	s_mov_b64 exec, -1
	v_xor_b32_e32 v244, s57, v2
	v_cmpx_gt_u32_e32 vcc, s86, v244
	v_lshrrev_b32_e32 v245, s87, v244
	v_lshl_add_u32 v245, v245, 2, v136
	ds_add_u32 v245, v135
	s_mov_b64 exec, -1
	v_xor_b32_e32 v246, s57, v3
	v_cmpx_gt_u32_e32 vcc, s86, v246
	v_lshrrev_b32_e32 v247, s87, v246
	v_lshl_add_u32 v247, v247, 2, v136
	ds_add_u32 v247, v135
	s_mov_b64 exec, -1
	v_xor_b32_e32 v240, s57, v4
	v_cmpx_gt_u32_e32 vcc, s86, v240
	v_lshrrev_b32_e32 v241, s87, v240
	v_lshl_add_u32 v241, v241, 2, v136
	ds_add_u32 v241, v135
	s_mov_b64 exec, -1
	v_xor_b32_e32 v242, s57, v5
	v_cmpx_gt_u32_e32 vcc, s86, v242
	v_lshrrev_b32_e32 v243, s87, v242
	v_lshl_add_u32 v243, v243, 2, v136
	ds_add_u32 v243, v135
	s_mov_b64 exec, -1
	v_xor_b32_e32 v244, s57, v6
	v_cmpx_gt_u32_e32 vcc, s86, v244
	v_lshrrev_b32_e32 v245, s87, v244
	v_lshl_add_u32 v245, v245, 2, v136
	ds_add_u32 v245, v135
	s_mov_b64 exec, -1
	v_xor_b32_e32 v246, s57, v7
	v_cmpx_gt_u32_e32 vcc, s86, v246
	v_lshrrev_b32_e32 v247, s87, v246
	v_lshl_add_u32 v247, v247, 2, v136
	ds_add_u32 v247, v135
	s_mov_b64 exec, -1
	v_xor_b32_e32 v240, s57, v8
	v_cmpx_gt_u32_e32 vcc, s86, v240
	v_lshrrev_b32_e32 v241, s87, v240
	v_lshl_add_u32 v241, v241, 2, v136
	ds_add_u32 v241, v135
	s_mov_b64 exec, -1
	v_xor_b32_e32 v242, s57, v9
	v_cmpx_gt_u32_e32 vcc, s86, v242
	v_lshrrev_b32_e32 v243, s87, v242
	v_lshl_add_u32 v243, v243, 2, v136
	ds_add_u32 v243, v135
	s_mov_b64 exec, -1
	v_xor_b32_e32 v244, s57, v10
	v_cmpx_gt_u32_e32 vcc, s86, v244
	v_lshrrev_b32_e32 v245, s87, v244
	v_lshl_add_u32 v245, v245, 2, v136
	ds_add_u32 v245, v135
	s_mov_b64 exec, -1
	v_xor_b32_e32 v246, s57, v11
	v_cmpx_gt_u32_e32 vcc, s86, v246
	v_lshrrev_b32_e32 v247, s87, v246
	v_lshl_add_u32 v247, v247, 2, v136
	ds_add_u32 v247, v135
	s_mov_b64 exec, -1
	v_xor_b32_e32 v240, s57, v12
	v_cmpx_gt_u32_e32 vcc, s86, v240
	v_lshrrev_b32_e32 v241, s87, v240
	v_lshl_add_u32 v241, v241, 2, v136
	ds_add_u32 v241, v135
	s_mov_b64 exec, -1
	v_xor_b32_e32 v242, s57, v13
	v_cmpx_gt_u32_e32 vcc, s86, v242
	v_lshrrev_b32_e32 v243, s87, v242
	v_lshl_add_u32 v243, v243, 2, v136
	ds_add_u32 v243, v135
	s_mov_b64 exec, -1
	v_xor_b32_e32 v244, s57, v14
	v_cmpx_gt_u32_e32 vcc, s86, v244
	v_lshrrev_b32_e32 v245, s87, v244
	v_lshl_add_u32 v245, v245, 2, v136
	ds_add_u32 v245, v135
	s_mov_b64 exec, -1
	v_xor_b32_e32 v246, s57, v15
	v_cmpx_gt_u32_e32 vcc, s86, v246
	v_lshrrev_b32_e32 v247, s87, v246
	v_lshl_add_u32 v247, v247, 2, v136
	ds_add_u32 v247, v135
	s_mov_b64 exec, -1
	s_cmpk_le_u32 s34, 16
	s_cbranch_scc1 .Lsel_hist_done
	v_xor_b32_e32 v240, s57, v16
	v_cmpx_gt_u32_e32 vcc, s86, v240
	v_lshrrev_b32_e32 v241, s87, v240
	v_lshl_add_u32 v241, v241, 2, v136
	ds_add_u32 v241, v135
	s_mov_b64 exec, -1
	v_xor_b32_e32 v242, s57, v17
	v_cmpx_gt_u32_e32 vcc, s86, v242
	v_lshrrev_b32_e32 v243, s87, v242
	v_lshl_add_u32 v243, v243, 2, v136
	ds_add_u32 v243, v135
	s_mov_b64 exec, -1
	v_xor_b32_e32 v244, s57, v18
	v_cmpx_gt_u32_e32 vcc, s86, v244
	v_lshrrev_b32_e32 v245, s87, v244
	v_lshl_add_u32 v245, v245, 2, v136
	ds_add_u32 v245, v135
	s_mov_b64 exec, -1
	v_xor_b32_e32 v246, s57, v19
	v_cmpx_gt_u32_e32 vcc, s86, v246
	v_lshrrev_b32_e32 v247, s87, v246
	v_lshl_add_u32 v247, v247, 2, v136
	ds_add_u32 v247, v135
	s_mov_b64 exec, -1
	v_xor_b32_e32 v240, s57, v20
	v_cmpx_gt_u32_e32 vcc, s86, v240
	v_lshrrev_b32_e32 v241, s87, v240
	v_lshl_add_u32 v241, v241, 2, v136
	ds_add_u32 v241, v135
	s_mov_b64 exec, -1
	v_xor_b32_e32 v242, s57, v21
	v_cmpx_gt_u32_e32 vcc, s86, v242
	v_lshrrev_b32_e32 v243, s87, v242
	v_lshl_add_u32 v243, v243, 2, v136
	ds_add_u32 v243, v135
	s_mov_b64 exec, -1
	v_xor_b32_e32 v244, s57, v22
	v_cmpx_gt_u32_e32 vcc, s86, v244
	v_lshrrev_b32_e32 v245, s87, v244
	v_lshl_add_u32 v245, v245, 2, v136
	ds_add_u32 v245, v135
	s_mov_b64 exec, -1
	v_xor_b32_e32 v246, s57, v23
	v_cmpx_gt_u32_e32 vcc, s86, v246
	v_lshrrev_b32_e32 v247, s87, v246
	v_lshl_add_u32 v247, v247, 2, v136
	ds_add_u32 v247, v135
	s_mov_b64 exec, -1
	v_xor_b32_e32 v240, s57, v24
	v_cmpx_gt_u32_e32 vcc, s86, v240
	v_lshrrev_b32_e32 v241, s87, v240
	v_lshl_add_u32 v241, v241, 2, v136
	ds_add_u32 v241, v135
	s_mov_b64 exec, -1
	v_xor_b32_e32 v242, s57, v25
	v_cmpx_gt_u32_e32 vcc, s86, v242
	v_lshrrev_b32_e32 v243, s87, v242
	v_lshl_add_u32 v243, v243, 2, v136
	ds_add_u32 v243, v135
	s_mov_b64 exec, -1
	v_xor_b32_e32 v244, s57, v26
	v_cmpx_gt_u32_e32 vcc, s86, v244
	v_lshrrev_b32_e32 v245, s87, v244
	v_lshl_add_u32 v245, v245, 2, v136
	ds_add_u32 v245, v135
	s_mov_b64 exec, -1
	v_xor_b32_e32 v246, s57, v27
	v_cmpx_gt_u32_e32 vcc, s86, v246
	v_lshrrev_b32_e32 v247, s87, v246
	v_lshl_add_u32 v247, v247, 2, v136
	ds_add_u32 v247, v135
	s_mov_b64 exec, -1
	v_xor_b32_e32 v240, s57, v28
	v_cmpx_gt_u32_e32 vcc, s86, v240
	v_lshrrev_b32_e32 v241, s87, v240
	v_lshl_add_u32 v241, v241, 2, v136
	ds_add_u32 v241, v135
	s_mov_b64 exec, -1
	v_xor_b32_e32 v242, s57, v29
	v_cmpx_gt_u32_e32 vcc, s86, v242
	v_lshrrev_b32_e32 v243, s87, v242
	v_lshl_add_u32 v243, v243, 2, v136
	ds_add_u32 v243, v135
	s_mov_b64 exec, -1
	v_xor_b32_e32 v244, s57, v30
	v_cmpx_gt_u32_e32 vcc, s86, v244
	v_lshrrev_b32_e32 v245, s87, v244
	v_lshl_add_u32 v245, v245, 2, v136
	ds_add_u32 v245, v135
	s_mov_b64 exec, -1
	v_xor_b32_e32 v246, s57, v31
	v_cmpx_gt_u32_e32 vcc, s86, v246
	v_lshrrev_b32_e32 v247, s87, v246
	v_lshl_add_u32 v247, v247, 2, v136
	ds_add_u32 v247, v135
	s_mov_b64 exec, -1
	s_cmpk_le_u32 s34, 32
	s_cbranch_scc1 .Lsel_hist_done
	v_xor_b32_e32 v240, s57, v32
	v_cmpx_gt_u32_e32 vcc, s86, v240
	v_lshrrev_b32_e32 v241, s87, v240
	v_lshl_add_u32 v241, v241, 2, v136
	ds_add_u32 v241, v135
	s_mov_b64 exec, -1
	v_xor_b32_e32 v242, s57, v33
	v_cmpx_gt_u32_e32 vcc, s86, v242
	v_lshrrev_b32_e32 v243, s87, v242
	v_lshl_add_u32 v243, v243, 2, v136
	ds_add_u32 v243, v135
	s_mov_b64 exec, -1
	v_xor_b32_e32 v244, s57, v34
	v_cmpx_gt_u32_e32 vcc, s86, v244
	v_lshrrev_b32_e32 v245, s87, v244
	v_lshl_add_u32 v245, v245, 2, v136
	ds_add_u32 v245, v135
	s_mov_b64 exec, -1
	v_xor_b32_e32 v246, s57, v35
	v_cmpx_gt_u32_e32 vcc, s86, v246
	v_lshrrev_b32_e32 v247, s87, v246
	v_lshl_add_u32 v247, v247, 2, v136
	ds_add_u32 v247, v135
	s_mov_b64 exec, -1
	v_xor_b32_e32 v240, s57, v36
	v_cmpx_gt_u32_e32 vcc, s86, v240
	v_lshrrev_b32_e32 v241, s87, v240
	v_lshl_add_u32 v241, v241, 2, v136
	ds_add_u32 v241, v135
	s_mov_b64 exec, -1
	v_xor_b32_e32 v242, s57, v37
	v_cmpx_gt_u32_e32 vcc, s86, v242
	v_lshrrev_b32_e32 v243, s87, v242
	v_lshl_add_u32 v243, v243, 2, v136
	ds_add_u32 v243, v135
	s_mov_b64 exec, -1
	v_xor_b32_e32 v244, s57, v38
	v_cmpx_gt_u32_e32 vcc, s86, v244
	v_lshrrev_b32_e32 v245, s87, v244
	v_lshl_add_u32 v245, v245, 2, v136
	ds_add_u32 v245, v135
	s_mov_b64 exec, -1
	v_xor_b32_e32 v246, s57, v39
	v_cmpx_gt_u32_e32 vcc, s86, v246
	v_lshrrev_b32_e32 v247, s87, v246
	v_lshl_add_u32 v247, v247, 2, v136
	ds_add_u32 v247, v135
	s_mov_b64 exec, -1
	v_xor_b32_e32 v240, s57, v40
	v_cmpx_gt_u32_e32 vcc, s86, v240
	v_lshrrev_b32_e32 v241, s87, v240
	v_lshl_add_u32 v241, v241, 2, v136
	ds_add_u32 v241, v135
	s_mov_b64 exec, -1
	v_xor_b32_e32 v242, s57, v41
	v_cmpx_gt_u32_e32 vcc, s86, v242
	v_lshrrev_b32_e32 v243, s87, v242
	v_lshl_add_u32 v243, v243, 2, v136
	ds_add_u32 v243, v135
	s_mov_b64 exec, -1
	v_xor_b32_e32 v244, s57, v42
	v_cmpx_gt_u32_e32 vcc, s86, v244
	v_lshrrev_b32_e32 v245, s87, v244
	v_lshl_add_u32 v245, v245, 2, v136
	ds_add_u32 v245, v135
	s_mov_b64 exec, -1
	v_xor_b32_e32 v246, s57, v43
	v_cmpx_gt_u32_e32 vcc, s86, v246
	v_lshrrev_b32_e32 v247, s87, v246
	v_lshl_add_u32 v247, v247, 2, v136
	ds_add_u32 v247, v135
	s_mov_b64 exec, -1
	v_xor_b32_e32 v240, s57, v44
	v_cmpx_gt_u32_e32 vcc, s86, v240
	v_lshrrev_b32_e32 v241, s87, v240
	v_lshl_add_u32 v241, v241, 2, v136
	ds_add_u32 v241, v135
	s_mov_b64 exec, -1
	v_xor_b32_e32 v242, s57, v45
	v_cmpx_gt_u32_e32 vcc, s86, v242
	v_lshrrev_b32_e32 v243, s87, v242
	v_lshl_add_u32 v243, v243, 2, v136
	ds_add_u32 v243, v135
	s_mov_b64 exec, -1
	v_xor_b32_e32 v244, s57, v46
	v_cmpx_gt_u32_e32 vcc, s86, v244
	v_lshrrev_b32_e32 v245, s87, v244
	v_lshl_add_u32 v245, v245, 2, v136
	ds_add_u32 v245, v135
	s_mov_b64 exec, -1
	v_xor_b32_e32 v246, s57, v47
	v_cmpx_gt_u32_e32 vcc, s86, v246
	v_lshrrev_b32_e32 v247, s87, v246
	v_lshl_add_u32 v247, v247, 2, v136
	ds_add_u32 v247, v135
	s_mov_b64 exec, -1
	s_cmpk_le_u32 s34, 48
	s_cbranch_scc1 .Lsel_hist_done
	v_xor_b32_e32 v240, s57, v48
	v_cmpx_gt_u32_e32 vcc, s86, v240
	v_lshrrev_b32_e32 v241, s87, v240
	v_lshl_add_u32 v241, v241, 2, v136
	ds_add_u32 v241, v135
	s_mov_b64 exec, -1
	v_xor_b32_e32 v242, s57, v49
	v_cmpx_gt_u32_e32 vcc, s86, v242
	v_lshrrev_b32_e32 v243, s87, v242
	v_lshl_add_u32 v243, v243, 2, v136
	ds_add_u32 v243, v135
	s_mov_b64 exec, -1
	v_xor_b32_e32 v244, s57, v50
	v_cmpx_gt_u32_e32 vcc, s86, v244
	v_lshrrev_b32_e32 v245, s87, v244
	v_lshl_add_u32 v245, v245, 2, v136
	ds_add_u32 v245, v135
	s_mov_b64 exec, -1
	v_xor_b32_e32 v246, s57, v51
	v_cmpx_gt_u32_e32 vcc, s86, v246
	v_lshrrev_b32_e32 v247, s87, v246
	v_lshl_add_u32 v247, v247, 2, v136
	ds_add_u32 v247, v135
	s_mov_b64 exec, -1
	v_xor_b32_e32 v240, s57, v52
	v_cmpx_gt_u32_e32 vcc, s86, v240
	v_lshrrev_b32_e32 v241, s87, v240
	v_lshl_add_u32 v241, v241, 2, v136
	ds_add_u32 v241, v135
	s_mov_b64 exec, -1
	v_xor_b32_e32 v242, s57, v53
	v_cmpx_gt_u32_e32 vcc, s86, v242
	v_lshrrev_b32_e32 v243, s87, v242
	v_lshl_add_u32 v243, v243, 2, v136
	ds_add_u32 v243, v135
	s_mov_b64 exec, -1
	v_xor_b32_e32 v244, s57, v54
	v_cmpx_gt_u32_e32 vcc, s86, v244
	v_lshrrev_b32_e32 v245, s87, v244
	v_lshl_add_u32 v245, v245, 2, v136
	ds_add_u32 v245, v135
	s_mov_b64 exec, -1
	v_xor_b32_e32 v246, s57, v55
	v_cmpx_gt_u32_e32 vcc, s86, v246
	v_lshrrev_b32_e32 v247, s87, v246
	v_lshl_add_u32 v247, v247, 2, v136
	ds_add_u32 v247, v135
	s_mov_b64 exec, -1
	v_xor_b32_e32 v240, s57, v56
	v_cmpx_gt_u32_e32 vcc, s86, v240
	v_lshrrev_b32_e32 v241, s87, v240
	v_lshl_add_u32 v241, v241, 2, v136
	ds_add_u32 v241, v135
	s_mov_b64 exec, -1
	v_xor_b32_e32 v242, s57, v57
	v_cmpx_gt_u32_e32 vcc, s86, v242
	v_lshrrev_b32_e32 v243, s87, v242
	v_lshl_add_u32 v243, v243, 2, v136
	ds_add_u32 v243, v135
	s_mov_b64 exec, -1
	v_xor_b32_e32 v244, s57, v58
	v_cmpx_gt_u32_e32 vcc, s86, v244
	v_lshrrev_b32_e32 v245, s87, v244
	v_lshl_add_u32 v245, v245, 2, v136
	ds_add_u32 v245, v135
	s_mov_b64 exec, -1
	v_xor_b32_e32 v246, s57, v59
	v_cmpx_gt_u32_e32 vcc, s86, v246
	v_lshrrev_b32_e32 v247, s87, v246
	v_lshl_add_u32 v247, v247, 2, v136
	ds_add_u32 v247, v135
	s_mov_b64 exec, -1
	v_xor_b32_e32 v240, s57, v60
	v_cmpx_gt_u32_e32 vcc, s86, v240
	v_lshrrev_b32_e32 v241, s87, v240
	v_lshl_add_u32 v241, v241, 2, v136
	ds_add_u32 v241, v135
	s_mov_b64 exec, -1
	v_xor_b32_e32 v242, s57, v61
	v_cmpx_gt_u32_e32 vcc, s86, v242
	v_lshrrev_b32_e32 v243, s87, v242
	v_lshl_add_u32 v243, v243, 2, v136
	ds_add_u32 v243, v135
	s_mov_b64 exec, -1
	v_xor_b32_e32 v244, s57, v62
	v_cmpx_gt_u32_e32 vcc, s86, v244
	v_lshrrev_b32_e32 v245, s87, v244
	v_lshl_add_u32 v245, v245, 2, v136
	ds_add_u32 v245, v135
	s_mov_b64 exec, -1
	v_xor_b32_e32 v246, s57, v63
	v_cmpx_gt_u32_e32 vcc, s86, v246
	v_lshrrev_b32_e32 v247, s87, v246
	v_lshl_add_u32 v247, v247, 2, v136
	ds_add_u32 v247, v135
	s_mov_b64 exec, -1
	s_cmpk_le_u32 s34, 64
	s_cbranch_scc1 .Lsel_hist_done
	v_xor_b32_e32 v240, s57, v64
	v_cmpx_gt_u32_e32 vcc, s86, v240
	v_lshrrev_b32_e32 v241, s87, v240
	v_lshl_add_u32 v241, v241, 2, v136
	ds_add_u32 v241, v135
	s_mov_b64 exec, -1
	v_xor_b32_e32 v242, s57, v65
	v_cmpx_gt_u32_e32 vcc, s86, v242
	v_lshrrev_b32_e32 v243, s87, v242
	v_lshl_add_u32 v243, v243, 2, v136
	ds_add_u32 v243, v135
	s_mov_b64 exec, -1
	v_xor_b32_e32 v244, s57, v66
	v_cmpx_gt_u32_e32 vcc, s86, v244
	v_lshrrev_b32_e32 v245, s87, v244
	v_lshl_add_u32 v245, v245, 2, v136
	ds_add_u32 v245, v135
	s_mov_b64 exec, -1
	v_xor_b32_e32 v246, s57, v67
	v_cmpx_gt_u32_e32 vcc, s86, v246
	v_lshrrev_b32_e32 v247, s87, v246
	v_lshl_add_u32 v247, v247, 2, v136
	ds_add_u32 v247, v135
	s_mov_b64 exec, -1
	v_xor_b32_e32 v240, s57, v68
	v_cmpx_gt_u32_e32 vcc, s86, v240
	v_lshrrev_b32_e32 v241, s87, v240
	v_lshl_add_u32 v241, v241, 2, v136
	ds_add_u32 v241, v135
	s_mov_b64 exec, -1
	v_xor_b32_e32 v242, s57, v69
	v_cmpx_gt_u32_e32 vcc, s86, v242
	v_lshrrev_b32_e32 v243, s87, v242
	v_lshl_add_u32 v243, v243, 2, v136
	ds_add_u32 v243, v135
	s_mov_b64 exec, -1
	v_xor_b32_e32 v244, s57, v70
	v_cmpx_gt_u32_e32 vcc, s86, v244
	v_lshrrev_b32_e32 v245, s87, v244
	v_lshl_add_u32 v245, v245, 2, v136
	ds_add_u32 v245, v135
	s_mov_b64 exec, -1
	v_xor_b32_e32 v246, s57, v71
	v_cmpx_gt_u32_e32 vcc, s86, v246
	v_lshrrev_b32_e32 v247, s87, v246
	v_lshl_add_u32 v247, v247, 2, v136
	ds_add_u32 v247, v135
	s_mov_b64 exec, -1
	v_xor_b32_e32 v240, s57, v72
	v_cmpx_gt_u32_e32 vcc, s86, v240
	v_lshrrev_b32_e32 v241, s87, v240
	v_lshl_add_u32 v241, v241, 2, v136
	ds_add_u32 v241, v135
	s_mov_b64 exec, -1
	v_xor_b32_e32 v242, s57, v73
	v_cmpx_gt_u32_e32 vcc, s86, v242
	v_lshrrev_b32_e32 v243, s87, v242
	v_lshl_add_u32 v243, v243, 2, v136
	ds_add_u32 v243, v135
	s_mov_b64 exec, -1
	v_xor_b32_e32 v244, s57, v74
	v_cmpx_gt_u32_e32 vcc, s86, v244
	v_lshrrev_b32_e32 v245, s87, v244
	v_lshl_add_u32 v245, v245, 2, v136
	ds_add_u32 v245, v135
	s_mov_b64 exec, -1
	v_xor_b32_e32 v246, s57, v75
	v_cmpx_gt_u32_e32 vcc, s86, v246
	v_lshrrev_b32_e32 v247, s87, v246
	v_lshl_add_u32 v247, v247, 2, v136
	ds_add_u32 v247, v135
	s_mov_b64 exec, -1
	v_xor_b32_e32 v240, s57, v76
	v_cmpx_gt_u32_e32 vcc, s86, v240
	v_lshrrev_b32_e32 v241, s87, v240
	v_lshl_add_u32 v241, v241, 2, v136
	ds_add_u32 v241, v135
	s_mov_b64 exec, -1
	v_xor_b32_e32 v242, s57, v77
	v_cmpx_gt_u32_e32 vcc, s86, v242
	v_lshrrev_b32_e32 v243, s87, v242
	v_lshl_add_u32 v243, v243, 2, v136
	ds_add_u32 v243, v135
	s_mov_b64 exec, -1
	v_xor_b32_e32 v244, s57, v78
	v_cmpx_gt_u32_e32 vcc, s86, v244
	v_lshrrev_b32_e32 v245, s87, v244
	v_lshl_add_u32 v245, v245, 2, v136
	ds_add_u32 v245, v135
	s_mov_b64 exec, -1
	v_xor_b32_e32 v246, s57, v79
	v_cmpx_gt_u32_e32 vcc, s86, v246
	v_lshrrev_b32_e32 v247, s87, v246
	v_lshl_add_u32 v247, v247, 2, v136
	ds_add_u32 v247, v135
	s_mov_b64 exec, -1
	s_cmpk_le_u32 s34, 80
	s_cbranch_scc1 .Lsel_hist_done
	v_xor_b32_e32 v240, s57, v80
	v_cmpx_gt_u32_e32 vcc, s86, v240
	v_lshrrev_b32_e32 v241, s87, v240
	v_lshl_add_u32 v241, v241, 2, v136
	ds_add_u32 v241, v135
	s_mov_b64 exec, -1
	v_xor_b32_e32 v242, s57, v81
	v_cmpx_gt_u32_e32 vcc, s86, v242
	v_lshrrev_b32_e32 v243, s87, v242
	v_lshl_add_u32 v243, v243, 2, v136
	ds_add_u32 v243, v135
	s_mov_b64 exec, -1
	v_xor_b32_e32 v244, s57, v82
	v_cmpx_gt_u32_e32 vcc, s86, v244
	v_lshrrev_b32_e32 v245, s87, v244
	v_lshl_add_u32 v245, v245, 2, v136
	ds_add_u32 v245, v135
	s_mov_b64 exec, -1
	v_xor_b32_e32 v246, s57, v83
	v_cmpx_gt_u32_e32 vcc, s86, v246
	v_lshrrev_b32_e32 v247, s87, v246
	v_lshl_add_u32 v247, v247, 2, v136
	ds_add_u32 v247, v135
	s_mov_b64 exec, -1
	v_xor_b32_e32 v240, s57, v84
	v_cmpx_gt_u32_e32 vcc, s86, v240
	v_lshrrev_b32_e32 v241, s87, v240
	v_lshl_add_u32 v241, v241, 2, v136
	ds_add_u32 v241, v135
	s_mov_b64 exec, -1
	v_xor_b32_e32 v242, s57, v85
	v_cmpx_gt_u32_e32 vcc, s86, v242
	v_lshrrev_b32_e32 v243, s87, v242
	v_lshl_add_u32 v243, v243, 2, v136
	ds_add_u32 v243, v135
	s_mov_b64 exec, -1
	v_xor_b32_e32 v244, s57, v86
	v_cmpx_gt_u32_e32 vcc, s86, v244
	v_lshrrev_b32_e32 v245, s87, v244
	v_lshl_add_u32 v245, v245, 2, v136
	ds_add_u32 v245, v135
	s_mov_b64 exec, -1
	v_xor_b32_e32 v246, s57, v87
	v_cmpx_gt_u32_e32 vcc, s86, v246
	v_lshrrev_b32_e32 v247, s87, v246
	v_lshl_add_u32 v247, v247, 2, v136
	ds_add_u32 v247, v135
	s_mov_b64 exec, -1
	v_xor_b32_e32 v240, s57, v88
	v_cmpx_gt_u32_e32 vcc, s86, v240
	v_lshrrev_b32_e32 v241, s87, v240
	v_lshl_add_u32 v241, v241, 2, v136
	ds_add_u32 v241, v135
	s_mov_b64 exec, -1
	v_xor_b32_e32 v242, s57, v89
	v_cmpx_gt_u32_e32 vcc, s86, v242
	v_lshrrev_b32_e32 v243, s87, v242
	v_lshl_add_u32 v243, v243, 2, v136
	ds_add_u32 v243, v135
	s_mov_b64 exec, -1
	v_xor_b32_e32 v244, s57, v90
	v_cmpx_gt_u32_e32 vcc, s86, v244
	v_lshrrev_b32_e32 v245, s87, v244
	v_lshl_add_u32 v245, v245, 2, v136
	ds_add_u32 v245, v135
	s_mov_b64 exec, -1
	v_xor_b32_e32 v246, s57, v91
	v_cmpx_gt_u32_e32 vcc, s86, v246
	v_lshrrev_b32_e32 v247, s87, v246
	v_lshl_add_u32 v247, v247, 2, v136
	ds_add_u32 v247, v135
	s_mov_b64 exec, -1
	v_xor_b32_e32 v240, s57, v92
	v_cmpx_gt_u32_e32 vcc, s86, v240
	v_lshrrev_b32_e32 v241, s87, v240
	v_lshl_add_u32 v241, v241, 2, v136
	ds_add_u32 v241, v135
	s_mov_b64 exec, -1
	v_xor_b32_e32 v242, s57, v93
	v_cmpx_gt_u32_e32 vcc, s86, v242
	v_lshrrev_b32_e32 v243, s87, v242
	v_lshl_add_u32 v243, v243, 2, v136
	ds_add_u32 v243, v135
	s_mov_b64 exec, -1
	v_xor_b32_e32 v244, s57, v94
	v_cmpx_gt_u32_e32 vcc, s86, v244
	v_lshrrev_b32_e32 v245, s87, v244
	v_lshl_add_u32 v245, v245, 2, v136
	ds_add_u32 v245, v135
	s_mov_b64 exec, -1
	v_xor_b32_e32 v246, s57, v95
	v_cmpx_gt_u32_e32 vcc, s86, v246
	v_lshrrev_b32_e32 v247, s87, v246
	v_lshl_add_u32 v247, v247, 2, v136
	ds_add_u32 v247, v135
	s_mov_b64 exec, -1
	s_cmpk_le_u32 s34, 96
	s_cbranch_scc1 .Lsel_hist_done
	v_xor_b32_e32 v240, s57, v208
	v_cmpx_gt_u32_e32 vcc, s86, v240
	v_lshrrev_b32_e32 v241, s87, v240
	v_lshl_add_u32 v241, v241, 2, v136
	ds_add_u32 v241, v135
	s_mov_b64 exec, -1
	v_xor_b32_e32 v242, s57, v209
	v_cmpx_gt_u32_e32 vcc, s86, v242
	v_lshrrev_b32_e32 v243, s87, v242
	v_lshl_add_u32 v243, v243, 2, v136
	ds_add_u32 v243, v135
	s_mov_b64 exec, -1
	v_xor_b32_e32 v244, s57, v210
	v_cmpx_gt_u32_e32 vcc, s86, v244
	v_lshrrev_b32_e32 v245, s87, v244
	v_lshl_add_u32 v245, v245, 2, v136
	ds_add_u32 v245, v135
	s_mov_b64 exec, -1
	v_xor_b32_e32 v246, s57, v211
	v_cmpx_gt_u32_e32 vcc, s86, v246
	v_lshrrev_b32_e32 v247, s87, v246
	v_lshl_add_u32 v247, v247, 2, v136
	ds_add_u32 v247, v135
	s_mov_b64 exec, -1
	v_xor_b32_e32 v240, s57, v212
	v_cmpx_gt_u32_e32 vcc, s86, v240
	v_lshrrev_b32_e32 v241, s87, v240
	v_lshl_add_u32 v241, v241, 2, v136
	ds_add_u32 v241, v135
	s_mov_b64 exec, -1
	v_xor_b32_e32 v242, s57, v213
	v_cmpx_gt_u32_e32 vcc, s86, v242
	v_lshrrev_b32_e32 v243, s87, v242
	v_lshl_add_u32 v243, v243, 2, v136
	ds_add_u32 v243, v135
	s_mov_b64 exec, -1
	v_xor_b32_e32 v244, s57, v214
	v_cmpx_gt_u32_e32 vcc, s86, v244
	v_lshrrev_b32_e32 v245, s87, v244
	v_lshl_add_u32 v245, v245, 2, v136
	ds_add_u32 v245, v135
	s_mov_b64 exec, -1
	v_xor_b32_e32 v246, s57, v215
	v_cmpx_gt_u32_e32 vcc, s86, v246
	v_lshrrev_b32_e32 v247, s87, v246
	v_lshl_add_u32 v247, v247, 2, v136
	ds_add_u32 v247, v135
	s_mov_b64 exec, -1
	v_xor_b32_e32 v240, s57, v216
	v_cmpx_gt_u32_e32 vcc, s86, v240
	v_lshrrev_b32_e32 v241, s87, v240
	v_lshl_add_u32 v241, v241, 2, v136
	ds_add_u32 v241, v135
	s_mov_b64 exec, -1
	v_xor_b32_e32 v242, s57, v217
	v_cmpx_gt_u32_e32 vcc, s86, v242
	v_lshrrev_b32_e32 v243, s87, v242
	v_lshl_add_u32 v243, v243, 2, v136
	ds_add_u32 v243, v135
	s_mov_b64 exec, -1
	v_xor_b32_e32 v244, s57, v218
	v_cmpx_gt_u32_e32 vcc, s86, v244
	v_lshrrev_b32_e32 v245, s87, v244
	v_lshl_add_u32 v245, v245, 2, v136
	ds_add_u32 v245, v135
	s_mov_b64 exec, -1
	v_xor_b32_e32 v246, s57, v219
	v_cmpx_gt_u32_e32 vcc, s86, v246
	v_lshrrev_b32_e32 v247, s87, v246
	v_lshl_add_u32 v247, v247, 2, v136
	ds_add_u32 v247, v135
	s_mov_b64 exec, -1
	v_xor_b32_e32 v240, s57, v220
	v_cmpx_gt_u32_e32 vcc, s86, v240
	v_lshrrev_b32_e32 v241, s87, v240
	v_lshl_add_u32 v241, v241, 2, v136
	ds_add_u32 v241, v135
	s_mov_b64 exec, -1
	v_xor_b32_e32 v242, s57, v221
	v_cmpx_gt_u32_e32 vcc, s86, v242
	v_lshrrev_b32_e32 v243, s87, v242
	v_lshl_add_u32 v243, v243, 2, v136
	ds_add_u32 v243, v135
	s_mov_b64 exec, -1
	v_xor_b32_e32 v244, s57, v222
	v_cmpx_gt_u32_e32 vcc, s86, v244
	v_lshrrev_b32_e32 v245, s87, v244
	v_lshl_add_u32 v245, v245, 2, v136
	ds_add_u32 v245, v135
	s_mov_b64 exec, -1
	v_xor_b32_e32 v246, s57, v223
	v_cmpx_gt_u32_e32 vcc, s86, v246
	v_lshrrev_b32_e32 v247, s87, v246
	v_lshl_add_u32 v247, v247, 2, v136
	ds_add_u32 v247, v135
	s_mov_b64 exec, -1
	s_cmpk_le_u32 s34, 112
	s_cbranch_scc1 .Lsel_hist_done
	v_xor_b32_e32 v240, s57, v224
	v_cmpx_gt_u32_e32 vcc, s86, v240
	v_lshrrev_b32_e32 v241, s87, v240
	v_lshl_add_u32 v241, v241, 2, v136
	ds_add_u32 v241, v135
	s_mov_b64 exec, -1
	v_xor_b32_e32 v242, s57, v225
	v_cmpx_gt_u32_e32 vcc, s86, v242
	v_lshrrev_b32_e32 v243, s87, v242
	v_lshl_add_u32 v243, v243, 2, v136
	ds_add_u32 v243, v135
	s_mov_b64 exec, -1
	v_xor_b32_e32 v244, s57, v226
	v_cmpx_gt_u32_e32 vcc, s86, v244
	v_lshrrev_b32_e32 v245, s87, v244
	v_lshl_add_u32 v245, v245, 2, v136
	ds_add_u32 v245, v135
	s_mov_b64 exec, -1
	v_xor_b32_e32 v246, s57, v227
	v_cmpx_gt_u32_e32 vcc, s86, v246
	v_lshrrev_b32_e32 v247, s87, v246
	v_lshl_add_u32 v247, v247, 2, v136
	ds_add_u32 v247, v135
	s_mov_b64 exec, -1
	v_xor_b32_e32 v240, s57, v228
	v_cmpx_gt_u32_e32 vcc, s86, v240
	v_lshrrev_b32_e32 v241, s87, v240
	v_lshl_add_u32 v241, v241, 2, v136
	ds_add_u32 v241, v135
	s_mov_b64 exec, -1
	v_xor_b32_e32 v242, s57, v229
	v_cmpx_gt_u32_e32 vcc, s86, v242
	v_lshrrev_b32_e32 v243, s87, v242
	v_lshl_add_u32 v243, v243, 2, v136
	ds_add_u32 v243, v135
	s_mov_b64 exec, -1
	v_xor_b32_e32 v244, s57, v230
	v_cmpx_gt_u32_e32 vcc, s86, v244
	v_lshrrev_b32_e32 v245, s87, v244
	v_lshl_add_u32 v245, v245, 2, v136
	ds_add_u32 v245, v135
	s_mov_b64 exec, -1
	v_xor_b32_e32 v246, s57, v231
	v_cmpx_gt_u32_e32 vcc, s86, v246
	v_lshrrev_b32_e32 v247, s87, v246
	v_lshl_add_u32 v247, v247, 2, v136
	ds_add_u32 v247, v135
	s_mov_b64 exec, -1
	v_xor_b32_e32 v240, s57, v232
	v_cmpx_gt_u32_e32 vcc, s86, v240
	v_lshrrev_b32_e32 v241, s87, v240
	v_lshl_add_u32 v241, v241, 2, v136
	ds_add_u32 v241, v135
	s_mov_b64 exec, -1
	v_xor_b32_e32 v242, s57, v233
	v_cmpx_gt_u32_e32 vcc, s86, v242
	v_lshrrev_b32_e32 v243, s87, v242
	v_lshl_add_u32 v243, v243, 2, v136
	ds_add_u32 v243, v135
	s_mov_b64 exec, -1
	v_xor_b32_e32 v244, s57, v234
	v_cmpx_gt_u32_e32 vcc, s86, v244
	v_lshrrev_b32_e32 v245, s87, v244
	v_lshl_add_u32 v245, v245, 2, v136
	ds_add_u32 v245, v135
	s_mov_b64 exec, -1
	v_xor_b32_e32 v246, s57, v235
	v_cmpx_gt_u32_e32 vcc, s86, v246
	v_lshrrev_b32_e32 v247, s87, v246
	v_lshl_add_u32 v247, v247, 2, v136
	ds_add_u32 v247, v135
	s_mov_b64 exec, -1
	v_xor_b32_e32 v240, s57, v236
	v_cmpx_gt_u32_e32 vcc, s86, v240
	v_lshrrev_b32_e32 v241, s87, v240
	v_lshl_add_u32 v241, v241, 2, v136
	ds_add_u32 v241, v135
	s_mov_b64 exec, -1
	v_xor_b32_e32 v242, s57, v237
	v_cmpx_gt_u32_e32 vcc, s86, v242
	v_lshrrev_b32_e32 v243, s87, v242
	v_lshl_add_u32 v243, v243, 2, v136
	ds_add_u32 v243, v135
	s_mov_b64 exec, -1
	v_xor_b32_e32 v244, s57, v238
	v_cmpx_gt_u32_e32 vcc, s86, v244
	v_lshrrev_b32_e32 v245, s87, v244
	v_lshl_add_u32 v245, v245, 2, v136
	ds_add_u32 v245, v135
	s_mov_b64 exec, -1
	v_xor_b32_e32 v246, s57, v239
	v_cmpx_gt_u32_e32 vcc, s86, v246
	v_lshrrev_b32_e32 v247, s87, v246
	v_lshl_add_u32 v247, v247, 2, v136
	ds_add_u32 v247, v135
	s_mov_b64 exec, -1

.Lsel_final:
	s_cmp_lg_u32 s56, s91
	s_cbranch_scc1 .Lsel_final_slow
	v_cmp_le_u32_e64 s[96:97], v0, s57
	v_cmp_le_u32_e64 s[54:55], v1, s57
	v_cmp_le_u32_e64 s[98:99], v2, s57
	v_cmp_le_u32_e64 s[52:53], v3, s57
	v_writelane_b32 v250, s96, 0
	v_writelane_b32 v251, s97, 0
	v_writelane_b32 v250, s54, 1
	v_writelane_b32 v251, s55, 1
	v_writelane_b32 v250, s98, 2
	v_writelane_b32 v251, s99, 2
	v_writelane_b32 v250, s52, 3
	v_writelane_b32 v251, s53, 3
	v_cmp_le_u32_e64 s[96:97], v4, s57
	v_cmp_le_u32_e64 s[54:55], v5, s57
	v_cmp_le_u32_e64 s[98:99], v6, s57
	v_cmp_le_u32_e64 s[52:53], v7, s57
	v_writelane_b32 v250, s96, 4
	v_writelane_b32 v251, s97, 4
	v_writelane_b32 v250, s54, 5
	v_writelane_b32 v251, s55, 5
	v_writelane_b32 v250, s98, 6
	v_writelane_b32 v251, s99, 6
	v_writelane_b32 v250, s52, 7
	v_writelane_b32 v251, s53, 7
	v_cmp_le_u32_e64 s[96:97], v8, s57
	v_cmp_le_u32_e64 s[54:55], v9, s57
	v_cmp_le_u32_e64 s[98:99], v10, s57
	v_cmp_le_u32_e64 s[52:53], v11, s57
	v_writelane_b32 v250, s96, 8
	v_writelane_b32 v251, s97, 8
	v_writelane_b32 v250, s54, 9
	v_writelane_b32 v251, s55, 9
	v_writelane_b32 v250, s98, 10
	v_writelane_b32 v251, s99, 10
	v_writelane_b32 v250, s52, 11
	v_writelane_b32 v251, s53, 11
	v_cmp_le_u32_e64 s[96:97], v12, s57
	v_cmp_le_u32_e64 s[54:55], v13, s57
	v_cmp_le_u32_e64 s[98:99], v14, s57
	v_cmp_le_u32_e64 s[52:53], v15, s57
	v_writelane_b32 v250, s96, 12
	v_writelane_b32 v251, s97, 12
	v_writelane_b32 v250, s54, 13
	v_writelane_b32 v251, s55, 13
	v_writelane_b32 v250, s98, 14
	v_writelane_b32 v251, s99, 14
	v_writelane_b32 v250, s52, 15
	v_writelane_b32 v251, s53, 15
	s_cmpk_le_u32 s34, 16
	s_cbranch_scc1 .Lsel_store
	v_cmp_le_u32_e64 s[96:97], v16, s57
	v_cmp_le_u32_e64 s[54:55], v17, s57
	v_cmp_le_u32_e64 s[98:99], v18, s57
	v_cmp_le_u32_e64 s[52:53], v19, s57
	v_writelane_b32 v250, s96, 16
	v_writelane_b32 v251, s97, 16
	v_writelane_b32 v250, s54, 17
	v_writelane_b32 v251, s55, 17
	v_writelane_b32 v250, s98, 18
	v_writelane_b32 v251, s99, 18
	v_writelane_b32 v250, s52, 19
	v_writelane_b32 v251, s53, 19
	v_cmp_le_u32_e64 s[96:97], v20, s57
	v_cmp_le_u32_e64 s[54:55], v21, s57
	v_cmp_le_u32_e64 s[98:99], v22, s57
	v_cmp_le_u32_e64 s[52:53], v23, s57
	v_writelane_b32 v250, s96, 20
	v_writelane_b32 v251, s97, 20
	v_writelane_b32 v250, s54, 21
	v_writelane_b32 v251, s55, 21
	v_writelane_b32 v250, s98, 22
	v_writelane_b32 v251, s99, 22
	v_writelane_b32 v250, s52, 23
	v_writelane_b32 v251, s53, 23
	v_cmp_le_u32_e64 s[96:97], v24, s57
	v_cmp_le_u32_e64 s[54:55], v25, s57
	v_cmp_le_u32_e64 s[98:99], v26, s57
	v_cmp_le_u32_e64 s[52:53], v27, s57
	v_writelane_b32 v250, s96, 24
	v_writelane_b32 v251, s97, 24
	v_writelane_b32 v250, s54, 25
	v_writelane_b32 v251, s55, 25
	v_writelane_b32 v250, s98, 26
	v_writelane_b32 v251, s99, 26
	v_writelane_b32 v250, s52, 27
	v_writelane_b32 v251, s53, 27
	v_cmp_le_u32_e64 s[96:97], v28, s57
	v_cmp_le_u32_e64 s[54:55], v29, s57
	v_cmp_le_u32_e64 s[98:99], v30, s57
	v_cmp_le_u32_e64 s[52:53], v31, s57
	v_writelane_b32 v250, s96, 28
	v_writelane_b32 v251, s97, 28
	v_writelane_b32 v250, s54, 29
	v_writelane_b32 v251, s55, 29
	v_writelane_b32 v250, s98, 30
	v_writelane_b32 v251, s99, 30
	v_writelane_b32 v250, s52, 31
	v_writelane_b32 v251, s53, 31
	s_cmpk_le_u32 s34, 32
	s_cbranch_scc1 .Lsel_store
	v_cmp_le_u32_e64 s[96:97], v32, s57
	v_cmp_le_u32_e64 s[54:55], v33, s57
	v_cmp_le_u32_e64 s[98:99], v34, s57
	v_cmp_le_u32_e64 s[52:53], v35, s57
	v_writelane_b32 v250, s96, 32
	v_writelane_b32 v251, s97, 32
	v_writelane_b32 v250, s54, 33
	v_writelane_b32 v251, s55, 33
	v_writelane_b32 v250, s98, 34
	v_writelane_b32 v251, s99, 34
	v_writelane_b32 v250, s52, 35
	v_writelane_b32 v251, s53, 35
	v_cmp_le_u32_e64 s[96:97], v36, s57
	v_cmp_le_u32_e64 s[54:55], v37, s57
	v_cmp_le_u32_e64 s[98:99], v38, s57
	v_cmp_le_u32_e64 s[52:53], v39, s57
	v_writelane_b32 v250, s96, 36
	v_writelane_b32 v251, s97, 36
	v_writelane_b32 v250, s54, 37
	v_writelane_b32 v251, s55, 37
	v_writelane_b32 v250, s98, 38
	v_writelane_b32 v251, s99, 38
	v_writelane_b32 v250, s52, 39
	v_writelane_b32 v251, s53, 39
	v_cmp_le_u32_e64 s[96:97], v40, s57
	v_cmp_le_u32_e64 s[54:55], v41, s57
	v_cmp_le_u32_e64 s[98:99], v42, s57
	v_cmp_le_u32_e64 s[52:53], v43, s57
	v_writelane_b32 v250, s96, 40
	v_writelane_b32 v251, s97, 40
	v_writelane_b32 v250, s54, 41
	v_writelane_b32 v251, s55, 41
	v_writelane_b32 v250, s98, 42
	v_writelane_b32 v251, s99, 42
	v_writelane_b32 v250, s52, 43
	v_writelane_b32 v251, s53, 43
	v_cmp_le_u32_e64 s[96:97], v44, s57
	v_cmp_le_u32_e64 s[54:55], v45, s57
	v_cmp_le_u32_e64 s[98:99], v46, s57
	v_cmp_le_u32_e64 s[52:53], v47, s57
	v_writelane_b32 v250, s96, 44
	v_writelane_b32 v251, s97, 44
	v_writelane_b32 v250, s54, 45
	v_writelane_b32 v251, s55, 45
	v_writelane_b32 v250, s98, 46
	v_writelane_b32 v251, s99, 46
	v_writelane_b32 v250, s52, 47
	v_writelane_b32 v251, s53, 47
	s_cmpk_le_u32 s34, 48
	s_cbranch_scc1 .Lsel_store
	v_cmp_le_u32_e64 s[96:97], v48, s57
	v_cmp_le_u32_e64 s[54:55], v49, s57
	v_cmp_le_u32_e64 s[98:99], v50, s57
	v_cmp_le_u32_e64 s[52:53], v51, s57
	v_writelane_b32 v250, s96, 48
	v_writelane_b32 v251, s97, 48
	v_writelane_b32 v250, s54, 49
	v_writelane_b32 v251, s55, 49
	v_writelane_b32 v250, s98, 50
	v_writelane_b32 v251, s99, 50
	v_writelane_b32 v250, s52, 51
	v_writelane_b32 v251, s53, 51
	v_cmp_le_u32_e64 s[96:97], v52, s57
	v_cmp_le_u32_e64 s[54:55], v53, s57
	v_cmp_le_u32_e64 s[98:99], v54, s57
	v_cmp_le_u32_e64 s[52:53], v55, s57
	v_writelane_b32 v250, s96, 52
	v_writelane_b32 v251, s97, 52
	v_writelane_b32 v250, s54, 53
	v_writelane_b32 v251, s55, 53
	v_writelane_b32 v250, s98, 54
	v_writelane_b32 v251, s99, 54
	v_writelane_b32 v250, s52, 55
	v_writelane_b32 v251, s53, 55
	v_cmp_le_u32_e64 s[96:97], v56, s57
	v_cmp_le_u32_e64 s[54:55], v57, s57
	v_cmp_le_u32_e64 s[98:99], v58, s57
	v_cmp_le_u32_e64 s[52:53], v59, s57
	v_writelane_b32 v250, s96, 56
	v_writelane_b32 v251, s97, 56
	v_writelane_b32 v250, s54, 57
	v_writelane_b32 v251, s55, 57
	v_writelane_b32 v250, s98, 58
	v_writelane_b32 v251, s99, 58
	v_writelane_b32 v250, s52, 59
	v_writelane_b32 v251, s53, 59
	v_cmp_le_u32_e64 s[96:97], v60, s57
	v_cmp_le_u32_e64 s[54:55], v61, s57
	v_cmp_le_u32_e64 s[98:99], v62, s57
	v_cmp_le_u32_e64 s[52:53], v63, s57
	v_writelane_b32 v250, s96, 60
	v_writelane_b32 v251, s97, 60
	v_writelane_b32 v250, s54, 61
	v_writelane_b32 v251, s55, 61
	v_writelane_b32 v250, s98, 62
	v_writelane_b32 v251, s99, 62
	v_writelane_b32 v250, s52, 63
	v_writelane_b32 v251, s53, 63
	s_cmpk_le_u32 s34, 64
	s_cbranch_scc1 .Lsel_store
	v_cmp_le_u32_e64 s[96:97], v64, s57
	v_cmp_le_u32_e64 s[54:55], v65, s57
	v_cmp_le_u32_e64 s[98:99], v66, s57
	v_cmp_le_u32_e64 s[52:53], v67, s57
	v_writelane_b32 v252, s96, 0
	v_writelane_b32 v253, s97, 0
	v_writelane_b32 v252, s54, 1
	v_writelane_b32 v253, s55, 1
	v_writelane_b32 v252, s98, 2
	v_writelane_b32 v253, s99, 2
	v_writelane_b32 v252, s52, 3
	v_writelane_b32 v253, s53, 3
	v_cmp_le_u32_e64 s[96:97], v68, s57
	v_cmp_le_u32_e64 s[54:55], v69, s57
	v_cmp_le_u32_e64 s[98:99], v70, s57
	v_cmp_le_u32_e64 s[52:53], v71, s57
	v_writelane_b32 v252, s96, 4
	v_writelane_b32 v253, s97, 4
	v_writelane_b32 v252, s54, 5
	v_writelane_b32 v253, s55, 5
	v_writelane_b32 v252, s98, 6
	v_writelane_b32 v253, s99, 6
	v_writelane_b32 v252, s52, 7
	v_writelane_b32 v253, s53, 7
	v_cmp_le_u32_e64 s[96:97], v72, s57
	v_cmp_le_u32_e64 s[54:55], v73, s57
	v_cmp_le_u32_e64 s[98:99], v74, s57
	v_cmp_le_u32_e64 s[52:53], v75, s57
	v_writelane_b32 v252, s96, 8
	v_writelane_b32 v253, s97, 8
	v_writelane_b32 v252, s54, 9
	v_writelane_b32 v253, s55, 9
	v_writelane_b32 v252, s98, 10
	v_writelane_b32 v253, s99, 10
	v_writelane_b32 v252, s52, 11
	v_writelane_b32 v253, s53, 11
	v_cmp_le_u32_e64 s[96:97], v76, s57
	v_cmp_le_u32_e64 s[54:55], v77, s57
	v_cmp_le_u32_e64 s[98:99], v78, s57
	v_cmp_le_u32_e64 s[52:53], v79, s57
	v_writelane_b32 v252, s96, 12
	v_writelane_b32 v253, s97, 12
	v_writelane_b32 v252, s54, 13
	v_writelane_b32 v253, s55, 13
	v_writelane_b32 v252, s98, 14
	v_writelane_b32 v253, s99, 14
	v_writelane_b32 v252, s52, 15
	v_writelane_b32 v253, s53, 15
	s_cmpk_le_u32 s34, 80
	s_cbranch_scc1 .Lsel_store
	v_cmp_le_u32_e64 s[96:97], v80, s57
	v_cmp_le_u32_e64 s[54:55], v81, s57
	v_cmp_le_u32_e64 s[98:99], v82, s57
	v_cmp_le_u32_e64 s[52:53], v83, s57
	v_writelane_b32 v252, s96, 16
	v_writelane_b32 v253, s97, 16
	v_writelane_b32 v252, s54, 17
	v_writelane_b32 v253, s55, 17
	v_writelane_b32 v252, s98, 18
	v_writelane_b32 v253, s99, 18
	v_writelane_b32 v252, s52, 19
	v_writelane_b32 v253, s53, 19
	v_cmp_le_u32_e64 s[96:97], v84, s57
	v_cmp_le_u32_e64 s[54:55], v85, s57
	v_cmp_le_u32_e64 s[98:99], v86, s57
	v_cmp_le_u32_e64 s[52:53], v87, s57
	v_writelane_b32 v252, s96, 20
	v_writelane_b32 v253, s97, 20
	v_writelane_b32 v252, s54, 21
	v_writelane_b32 v253, s55, 21
	v_writelane_b32 v252, s98, 22
	v_writelane_b32 v253, s99, 22
	v_writelane_b32 v252, s52, 23
	v_writelane_b32 v253, s53, 23
	v_cmp_le_u32_e64 s[96:97], v88, s57
	v_cmp_le_u32_e64 s[54:55], v89, s57
	v_cmp_le_u32_e64 s[98:99], v90, s57
	v_cmp_le_u32_e64 s[52:53], v91, s57
	v_writelane_b32 v252, s96, 24
	v_writelane_b32 v253, s97, 24
	v_writelane_b32 v252, s54, 25
	v_writelane_b32 v253, s55, 25
	v_writelane_b32 v252, s98, 26
	v_writelane_b32 v253, s99, 26
	v_writelane_b32 v252, s52, 27
	v_writelane_b32 v253, s53, 27
	v_cmp_le_u32_e64 s[96:97], v92, s57
	v_cmp_le_u32_e64 s[54:55], v93, s57
	v_cmp_le_u32_e64 s[98:99], v94, s57
	v_cmp_le_u32_e64 s[52:53], v95, s57
	v_writelane_b32 v252, s96, 28
	v_writelane_b32 v253, s97, 28
	v_writelane_b32 v252, s54, 29
	v_writelane_b32 v253, s55, 29
	v_writelane_b32 v252, s98, 30
	v_writelane_b32 v253, s99, 30
	v_writelane_b32 v252, s52, 31
	v_writelane_b32 v253, s53, 31
	s_cmpk_le_u32 s34, 96
	s_cbranch_scc1 .Lsel_store
	v_cmp_le_u32_e64 s[96:97], v208, s57
	v_cmp_le_u32_e64 s[54:55], v209, s57
	v_cmp_le_u32_e64 s[98:99], v210, s57
	v_cmp_le_u32_e64 s[52:53], v211, s57
	v_writelane_b32 v252, s96, 32
	v_writelane_b32 v253, s97, 32
	v_writelane_b32 v252, s54, 33
	v_writelane_b32 v253, s55, 33
	v_writelane_b32 v252, s98, 34
	v_writelane_b32 v253, s99, 34
	v_writelane_b32 v252, s52, 35
	v_writelane_b32 v253, s53, 35
	v_cmp_le_u32_e64 s[96:97], v212, s57
	v_cmp_le_u32_e64 s[54:55], v213, s57
	v_cmp_le_u32_e64 s[98:99], v214, s57
	v_cmp_le_u32_e64 s[52:53], v215, s57
	v_writelane_b32 v252, s96, 36
	v_writelane_b32 v253, s97, 36
	v_writelane_b32 v252, s54, 37
	v_writelane_b32 v253, s55, 37
	v_writelane_b32 v252, s98, 38
	v_writelane_b32 v253, s99, 38
	v_writelane_b32 v252, s52, 39
	v_writelane_b32 v253, s53, 39
	v_cmp_le_u32_e64 s[96:97], v216, s57
	v_cmp_le_u32_e64 s[54:55], v217, s57
	v_cmp_le_u32_e64 s[98:99], v218, s57
	v_cmp_le_u32_e64 s[52:53], v219, s57
	v_writelane_b32 v252, s96, 40
	v_writelane_b32 v253, s97, 40
	v_writelane_b32 v252, s54, 41
	v_writelane_b32 v253, s55, 41
	v_writelane_b32 v252, s98, 42
	v_writelane_b32 v253, s99, 42
	v_writelane_b32 v252, s52, 43
	v_writelane_b32 v253, s53, 43
	v_cmp_le_u32_e64 s[96:97], v220, s57
	v_cmp_le_u32_e64 s[54:55], v221, s57
	v_cmp_le_u32_e64 s[98:99], v222, s57
	v_cmp_le_u32_e64 s[52:53], v223, s57
	v_writelane_b32 v252, s96, 44
	v_writelane_b32 v253, s97, 44
	v_writelane_b32 v252, s54, 45
	v_writelane_b32 v253, s55, 45
	v_writelane_b32 v252, s98, 46
	v_writelane_b32 v253, s99, 46
	v_writelane_b32 v252, s52, 47
	v_writelane_b32 v253, s53, 47
	s_cmpk_le_u32 s34, 112
	s_cbranch_scc1 .Lsel_store
	v_cmp_le_u32_e64 s[96:97], v224, s57
	v_cmp_le_u32_e64 s[54:55], v225, s57
	v_cmp_le_u32_e64 s[98:99], v226, s57
	v_cmp_le_u32_e64 s[52:53], v227, s57
	v_writelane_b32 v252, s96, 48
	v_writelane_b32 v253, s97, 48
	v_writelane_b32 v252, s54, 49
	v_writelane_b32 v253, s55, 49
	v_writelane_b32 v252, s98, 50
	v_writelane_b32 v253, s99, 50
	v_writelane_b32 v252, s52, 51
	v_writelane_b32 v253, s53, 51
	v_cmp_le_u32_e64 s[96:97], v228, s57
	v_cmp_le_u32_e64 s[54:55], v229, s57
	v_cmp_le_u32_e64 s[98:99], v230, s57
	v_cmp_le_u32_e64 s[52:53], v231, s57
	v_writelane_b32 v252, s96, 52
	v_writelane_b32 v253, s97, 52
	v_writelane_b32 v252, s54, 53
	v_writelane_b32 v253, s55, 53
	v_writelane_b32 v252, s98, 54
	v_writelane_b32 v253, s99, 54
	v_writelane_b32 v252, s52, 55
	v_writelane_b32 v253, s53, 55
	v_cmp_le_u32_e64 s[96:97], v232, s57
	v_cmp_le_u32_e64 s[54:55], v233, s57
	v_cmp_le_u32_e64 s[98:99], v234, s57
	v_cmp_le_u32_e64 s[52:53], v235, s57
	v_writelane_b32 v252, s96, 56
	v_writelane_b32 v253, s97, 56
	v_writelane_b32 v252, s54, 57
	v_writelane_b32 v253, s55, 57
	v_writelane_b32 v252, s98, 58
	v_writelane_b32 v253, s99, 58
	v_writelane_b32 v252, s52, 59
	v_writelane_b32 v253, s53, 59
	v_cmp_le_u32_e64 s[96:97], v236, s57
	v_cmp_le_u32_e64 s[54:55], v237, s57
	v_cmp_le_u32_e64 s[98:99], v238, s57
	v_cmp_le_u32_e64 s[52:53], v239, s57
	v_writelane_b32 v252, s96, 60
	v_writelane_b32 v253, s97, 60
	v_writelane_b32 v252, s54, 61
	v_writelane_b32 v253, s55, 61
	v_writelane_b32 v252, s98, 62
	v_writelane_b32 v253, s99, 62
	v_writelane_b32 v252, s52, 63
	v_writelane_b32 v253, s53, 63
	s_branch .Lsel_store

.LBB0_2681:
	global_load_dwordx4 v[0:3], v[48:49], off offset:1024
	global_load_dwordx4 v[4:7], v[48:49], off offset:2048
	global_load_dwordx4 v[12:15], v[48:49], off offset:3072
	global_load_dwordx4 v[8:11], v[48:49], off
	global_load_dwordx4 v[72:75], v[16:17], off
	global_load_dwordx4 v[76:79], v[18:19], off
	v_add_u32_e32 v148, s2, v148
	v_lshl_add_u64 v[48:49], v[48:49], 0, s[4:5]
	s_waitcnt vmcnt(0)
	global_load_dwordx4 v[170:173], v[20:21], off
	global_load_dwordx4 v[174:177], v[22:23], off
	global_load_dwordx4 v[178:181], v[24:25], off
	global_load_dwordx4 v[182:185], v[26:27], off
	global_load_dwordx4 v[186:189], v[28:29], off
	global_load_dwordx4 v[190:193], v[30:31], off
	global_load_dwordx4 v[194:197], v[32:33], off
	global_load_dwordx4 v[198:201], v[34:35], off
	global_load_dwordx4 v[202:205], v[36:37], off
	global_load_dwordx4 v[206:209], v[38:39], off
	global_load_dwordx4 v[210:213], v[40:41], off
	global_load_dwordx4 v[214:217], v[42:43], off
	global_load_dwordx4 v[218:221], v[44:45], off
	global_load_dwordx4 v[222:225], v[46:47], off
	v_lshlrev_b32_e32 v80, 16, v2
	v_and_b32_e32 v81, 0xffff0000, v2
	v_lshlrev_b32_e32 v52, 16, v12
	v_lshlrev_b32_e32 v85, 16, v8
	v_lshlrev_b32_e32 v84, 16, v10
	v_and_b32_e32 v87, 0xffff0000, v8
	v_and_b32_e32 v86, 0xffff0000, v10
	v_lshlrev_b32_e32 v89, 16, v9
	v_lshlrev_b32_e32 v88, 16, v11
	v_and_b32_e32 v91, 0xffff0000, v9
	v_and_b32_e32 v90, 0xffff0000, v11
	v_and_b32_e32 v53, 0xffff0000, v12
	v_lshlrev_b32_e32 v54, 16, v13
	v_and_b32_e32 v55, 0xffff0000, v13
	v_lshlrev_b32_e32 v11, 16, v1
	v_lshlrev_b32_e32 v10, 16, v0
	v_and_b32_e32 v9, 0xffff0000, v1
	v_and_b32_e32 v8, 0xffff0000, v0
	v_pk_add_f32 v[92:93], v[84:85], v[86:87]
	v_pk_add_f32 v[94:95], v[88:89], v[90:91]
	v_lshlrev_b32_e32 v82, 16, v3
	v_and_b32_e32 v83, 0xffff0000, v3
	v_lshlrev_b32_e32 v2, 16, v14
	v_and_b32_e32 v12, 0xffff0000, v14
	v_pk_add_f32 v[96:97], v[10:11], v[8:9]
	v_add_f32_e32 v3, v52, v53
	v_add_f32_e32 v13, v54, v55
	v_pk_add_f32 v[92:93], v[92:93], v[94:95]
	v_pk_add_f32 v[94:95], v[96:97], v[96:97] op_sel_hi:[0,1]
	v_pk_add_f32 v[100:101], v[2:3], v[12:13]
	v_add_f32_e32 v3, 0, v93
	v_lshlrev_b32_e32 v56, 16, v4
	v_and_b32_e32 v60, 0xffff0000, v4
	v_lshlrev_b32_e32 v58, 16, v5
	v_and_b32_e32 v62, 0xffff0000, v5
	v_add_f32_e32 v57, v80, v81
	v_add_f32_e32 v61, v82, v83
	v_mov_b32_e32 v59, v95
	v_add_f32_e32 v63, v92, v3
	v_lshlrev_b32_e32 v1, 16, v7
	v_lshlrev_b32_e32 v0, 16, v6
	v_and_b32_e32 v7, 0xffff0000, v7
	v_and_b32_e32 v6, 0xffff0000, v6
	v_pk_add_f32 v[96:97], v[56:57], v[60:61]
	v_pk_add_f32 v[92:93], v[58:59], v[62:63]
	v_pk_add_f32 v[98:99], v[0:1], v[6:7]
	v_pk_add_f32 v[92:93], v[96:97], v[92:93]
	v_pk_add_f32 v[98:99], v[98:99], v[98:99] op_sel_hi:[0,1]
	v_pk_add_f32 v[92:93], v[92:93], v[92:93] op_sel_hi:[0,1]
	v_lshlrev_b32_e32 v4, 16, v15
	v_and_b32_e32 v14, 0xffff0000, v15
	v_mov_b32_e32 v5, v99
	v_mov_b32_e32 v15, v93
	v_pk_add_f32 v[92:93], v[4:5], v[14:15]
	s_nop 0
	v_pk_add_f32 v[92:93], v[100:101], v[92:93]
	s_nop 0
	v_add_f32_e32 v3, v92, v93
	ds_bpermute_b32 v5, v64, v3
	s_waitcnt lgkmcnt(0)
	v_add_f32_e32 v3, v3, v5
	ds_bpermute_b32 v5, v65, v3
	s_waitcnt lgkmcnt(0)
	v_add_f32_e32 v3, v3, v5
	ds_bpermute_b32 v5, v66, v3
	s_waitcnt lgkmcnt(0)
	v_add_f32_e32 v3, v3, v5
	ds_bpermute_b32 v5, v67, v3
	s_waitcnt lgkmcnt(0)
	v_add_f32_e32 v3, v3, v5
	ds_bpermute_b32 v5, v68, v3
	s_waitcnt lgkmcnt(0)
	v_add_f32_e32 v3, v3, v5
	ds_bpermute_b32 v5, v69, v3
	s_waitcnt lgkmcnt(0)
	v_add_f32_e32 v3, v3, v5
	v_fmac_f32_e32 v91, 0xba000000, v3
	v_fmac_f32_e32 v87, 0xba000000, v3
	v_fmac_f32_e32 v90, 0xba000000, v3
	v_fmac_f32_e32 v86, 0xba000000, v3
	v_fmac_f32_e32 v8, 0xba000000, v3
	v_fmac_f32_e32 v9, 0xba000000, v3
	v_fmac_f32_e32 v11, 0xba000000, v3
	v_fmac_f32_e32 v89, 0xba000000, v3
	v_fmac_f32_e32 v85, 0xba000000, v3
	v_fmac_f32_e32 v88, 0xba000000, v3
	v_fmac_f32_e32 v84, 0xba000000, v3
	v_fmac_f32_e32 v10, 0xba000000, v3
	v_mov_b32_e32 v96, v87
	v_mov_b32_e32 v97, v86
	v_mov_b32_e32 v102, v91
	v_mov_b32_e32 v103, v90
	v_mov_b32_e32 v104, v11
	v_mov_b32_e32 v105, v9
	v_mov_b32_e32 v11, v8
	v_mov_b32_e32 v94, v85
	v_mov_b32_e32 v95, v84
	v_mov_b32_e32 v100, v89
	v_mov_b32_e32 v101, v88
	v_pk_mul_f32 v[96:97], v[96:97], v[96:97]
	v_pk_mul_f32 v[102:103], v[102:103], v[102:103]
	v_pk_mul_f32 v[112:113], v[104:105], v[104:105]
	v_pk_mul_f32 v[114:115], v[10:11], v[10:11]
	v_fmac_f32_e32 v80, 0xba000000, v3
	v_fmac_f32_e32 v82, 0xba000000, v3
	v_pk_fma_f32 v[94:95], v[94:95], v[94:95], v[96:97]
	v_pk_fma_f32 v[96:97], v[100:101], v[100:101], v[102:103]
	v_pk_mov_b32 v[100:101], v[114:115], v[112:113] op_sel:[1,0]
	v_mov_b32_e32 v115, v113
	v_fmac_f32_e32 v81, 0xba000000, v3
	v_fmac_f32_e32 v83, 0xba000000, v3
	v_fmac_f32_e32 v6, 0xba000000, v3
	v_fmac_f32_e32 v7, 0xba000000, v3
	v_fmac_f32_e32 v1, 0xba000000, v3
	v_mul_f32_e32 v8, v80, v80
	v_mul_f32_e32 v106, v82, v82
	v_pk_add_f32 v[94:95], v[94:95], v[96:97]
	v_pk_add_f32 v[96:97], v[100:101], v[114:115]
	v_fmac_f32_e32 v62, 0xba000000, v3
	v_fmac_f32_e32 v58, 0xba000000, v3
	v_fmac_f32_e32 v60, 0xba000000, v3
	v_fmac_f32_e32 v56, 0xba000000, v3
	v_fmac_f32_e32 v0, 0xba000000, v3
	v_mov_b32_e32 v108, v1
	v_mov_b32_e32 v109, v7
	v_mov_b32_e32 v1, v6
	v_pk_fma_f32 v[8:9], v[80:81], v[80:81], v[8:9] op_sel_hi:[1,1,0]
	v_pk_fma_f32 v[106:107], v[82:83], v[82:83], v[106:107] op_sel_hi:[1,1,0]
	v_pk_add_f32 v[94:95], v[94:95], v[94:95] op_sel_hi:[0,1]
	v_pk_add_f32 v[96:97], v[96:97], v[96:97] op_sel_hi:[0,1]
	v_pk_mul_f32 v[116:117], v[108:109], v[108:109]
	v_pk_mul_f32 v[118:119], v[0:1], v[0:1]
	v_mul_f32_e32 v8, v56, v56
	v_mul_f32_e32 v106, v60, v60
	v_mul_f32_e32 v96, v58, v58
	v_mul_f32_e32 v94, v62, v62
	v_fmac_f32_e32 v52, 0xba000000, v3
	v_fmac_f32_e32 v54, 0xba000000, v3
	v_pk_mov_b32 v[102:103], v[118:119], v[116:117] op_sel:[1,0]
	v_mov_b32_e32 v119, v117
	v_pk_add_f32 v[8:9], v[8:9], v[106:107]
	v_pk_add_f32 v[94:95], v[96:97], v[94:95]
	v_fmac_f32_e32 v53, 0xba000000, v3
	v_fmac_f32_e32 v55, 0xba000000, v3
	v_mul_f32_e32 v6, v52, v52
	v_mul_f32_e32 v110, v54, v54
	v_pk_add_f32 v[100:101], v[102:103], v[118:119]
	v_pk_add_f32 v[8:9], v[8:9], v[94:95]
	v_fmac_f32_e32 v14, 0xba000000, v3
	v_fmac_f32_e32 v4, 0xba000000, v3
	v_fmac_f32_e32 v12, 0xba000000, v3
	v_fmac_f32_e32 v2, 0xba000000, v3
	v_pk_fma_f32 v[6:7], v[52:53], v[52:53], v[6:7] op_sel_hi:[1,1,0]
	v_pk_fma_f32 v[110:111], v[54:55], v[54:55], v[110:111] op_sel_hi:[1,1,0]
	v_pk_add_f32 v[100:101], v[100:101], v[100:101] op_sel_hi:[0,1]
	v_pk_add_f32 v[8:9], v[8:9], v[8:9] op_sel_hi:[0,1]
	v_mul_f32_e32 v6, v2, v2
	v_mul_f32_e32 v110, v12, v12
	v_mul_f32_e32 v100, v4, v4
	v_mul_f32_e32 v8, v14, v14
	v_pk_add_f32 v[6:7], v[6:7], v[110:111]
	v_pk_add_f32 v[8:9], v[100:101], v[8:9]
	v_mov_b32_e32 v92, v85
	v_pk_add_f32 v[6:7], v[6:7], v[8:9]
	v_mov_b32_e32 v93, v87
	v_add_f32_e32 v3, v6, v7
	ds_bpermute_b32 v5, v64, v3
	v_mov_b32_e32 v98, v89
	v_mov_b32_e32 v99, v91
	v_mov_b32_e32 v85, v86
	v_mov_b32_e32 v89, v90
	s_waitcnt lgkmcnt(0)
	v_add_f32_e32 v3, v3, v5
	ds_bpermute_b32 v5, v65, v3
	v_mov_b32_e32 v59, v62
	v_mov_b32_e32 v57, v60
	s_waitcnt lgkmcnt(0)
	v_add_f32_e32 v3, v3, v5
	ds_bpermute_b32 v5, v66, v3
	s_waitcnt lgkmcnt(0)
	v_add_f32_e32 v3, v3, v5
	ds_bpermute_b32 v5, v67, v3
	s_waitcnt lgkmcnt(0)
	v_add_f32_e32 v3, v3, v5
	ds_bpermute_b32 v5, v68, v3
	s_waitcnt lgkmcnt(0)
	v_add_f32_e32 v3, v3, v5
	ds_bpermute_b32 v5, v69, v3
	s_waitcnt lgkmcnt(0)
	v_add_f32_e32 v3, v3, v5
	v_fmamk_f32 v3, v3, 0x3a000000, v70
	v_mul_f32_e32 v5, 0x4f800000, v3
	v_cmp_gt_f32_e32 vcc, s3, v3
	s_nop 1
	v_cndmask_b32_e32 v3, v3, v5, vcc
	v_sqrt_f32_e32 v5, v3
	s_nop 0
	v_add_u32_e32 v6, -1, v5
	v_add_u32_e32 v7, 1, v5
	v_fma_f32 v8, -v6, v5, v3
	v_fma_f32 v9, -v7, v5, v3
	v_cmp_ge_f32_e64 s[0:1], 0, v8
	s_nop 1
	v_cndmask_b32_e64 v5, v5, v6, s[0:1]
	v_cmp_lt_f32_e64 s[0:1], 0, v9
	s_nop 1
	v_cndmask_b32_e64 v5, v5, v7, s[0:1]
	v_mul_f32_e32 v6, 0x37800000, v5
	v_cndmask_b32_e32 v5, v5, v6, vcc
	v_cmp_class_f32_e32 vcc, v3, v71
	s_nop 1
	v_cndmask_b32_e32 v3, v5, v3, vcc
	v_div_scale_f32 v5, s[0:1], v3, v3, 1.0
	v_rcp_f32_e32 v7, v5
	v_div_scale_f32 v6, vcc, 1.0, v3, 1.0
	v_fma_f32 v8, -v5, v7, 1.0
	v_fmac_f32_e32 v7, v8, v7
	v_mul_f32_e32 v8, v6, v7
	v_fma_f32 v9, -v5, v8, v6
	v_fmac_f32_e32 v8, v9, v7
	v_fma_f32 v5, -v5, v8, v6
	v_div_fmas_f32 v5, v5, v7, v8
	v_div_fixup_f32 v94, v5, v3, 1.0
	v_pk_mul_f32 v[6:7], v[92:93], v[94:95] op_sel_hi:[1,0]
	v_pk_mul_f32 v[8:9], v[98:99], v[94:95] op_sel_hi:[1,0]
	v_pk_fma_f32 v[6:7], v[72:73], v[6:7], v[76:77]
	v_pk_fma_f32 v[8:9], v[74:75], v[8:9], v[78:79]
	global_store_dwordx4 v[50:51], v[6:9], off offset:-4096
	s_nop 0
	v_pk_mul_f32 v[76:77], v[88:89], v[94:95] op_sel_hi:[1,0]
	v_pk_mul_f32 v[78:79], v[84:85], v[94:95] op_sel_hi:[1,0]
	v_pk_mul_f32 v[10:11], v[10:11], v[94:95] op_sel_hi:[1,0]
	v_pk_mul_f32 v[56:57], v[56:57], v[94:95] op_sel_hi:[1,0]
	v_pk_mul_f32 v[0:1], v[0:1], v[94:95] op_sel_hi:[1,0]
	v_mov_b32_e32 v5, v14
	v_mov_b32_e32 v3, v12
	v_pk_mul_f32 v[4:5], v[4:5], v[94:95] op_sel_hi:[1,0]
	v_cmp_lt_i32_e32 vcc, s10, v148
	s_or_b64 s[8:9], vcc, s[8:9]
	s_waitcnt vmcnt(13)
	v_pk_fma_f32 v[6:7], v[170:171], v[78:79], v[174:175]
	v_pk_fma_f32 v[8:9], v[172:173], v[76:77], v[176:177]
	global_store_dwordx4 v[50:51], v[6:9], off offset:-4080
	s_nop 0
	v_pk_mul_f32 v[76:77], v[104:105], v[94:95] op_sel_hi:[1,0]
	s_waitcnt vmcnt(12)
	v_pk_fma_f32 v[6:7], v[178:179], v[10:11], v[182:183]
	v_pk_fma_f32 v[8:9], v[180:181], v[76:77], v[184:185]
	global_store_dwordx4 v[50:51], v[6:9], off offset:-2048
	s_nop 0
	v_pk_mul_f32 v[10:11], v[82:83], v[94:95] op_sel_hi:[1,0]
	v_pk_mul_f32 v[76:77], v[80:81], v[94:95] op_sel_hi:[1,0]
	s_waitcnt vmcnt(11)
	v_pk_fma_f32 v[8:9], v[188:189], v[10:11], v[192:193]
	v_pk_fma_f32 v[6:7], v[186:187], v[76:77], v[190:191]
	global_store_dwordx4 v[50:51], v[6:9], off offset:-2032
	s_nop 0
	v_pk_mul_f32 v[10:11], v[58:59], v[94:95] op_sel_hi:[1,0]
	s_waitcnt vmcnt(10)
	v_pk_fma_f32 v[6:7], v[194:195], v[56:57], v[198:199]
	v_pk_fma_f32 v[8:9], v[196:197], v[10:11], v[200:201]
	global_store_dwordx4 v[50:51], v[6:9], off
	s_nop 0
	v_pk_mul_f32 v[10:11], v[108:109], v[94:95] op_sel_hi:[1,0]
	s_waitcnt vmcnt(9)
	v_pk_fma_f32 v[6:7], v[202:203], v[0:1], v[206:207]
	v_pk_fma_f32 v[8:9], v[204:205], v[10:11], v[208:209]
	global_store_dwordx4 v[50:51], v[6:9], off offset:16
	s_nop 0
	v_pk_mul_f32 v[0:1], v[54:55], v[94:95] op_sel_hi:[1,0]
	v_pk_mul_f32 v[10:11], v[52:53], v[94:95] op_sel_hi:[1,0]
	s_waitcnt vmcnt(8)
	v_pk_fma_f32 v[8:9], v[212:213], v[0:1], v[216:217]
	v_pk_fma_f32 v[6:7], v[210:211], v[10:11], v[214:215]
	global_store_dwordx4 v[50:51], v[6:9], off offset:2048
	s_nop 0
	v_pk_mul_f32 v[0:1], v[2:3], v[94:95] op_sel_hi:[1,0]
	s_waitcnt vmcnt(7)
	v_pk_fma_f32 v[2:3], v[220:221], v[4:5], v[224:225]
	v_pk_fma_f32 v[0:1], v[218:219], v[0:1], v[222:223]
	global_store_dwordx4 v[50:51], v[0:3], off offset:2064
	v_lshl_add_u64 v[50:51], v[50:51], 0, s[6:7]
	s_andn2_b64 exec, exec, s[8:9]
	s_cbranch_execnz .LBB0_2681
